# GEMM K-loops: no per-segment toggles; one static s_setprio 1 for waves 4-7 for the duration of each K-loop
# baseline (speedup 1.0000x reference)
.LBB0_252:
	s_ashr_i32 s19, s18, 31
	s_lshl_b64 s[0:1], s[18:19], 19
	s_add_u32 s20, s33, s0
	s_addc_u32 s21, s34, s1
	s_and_b64 s[0:1], s[4:5], exec
	s_cselect_b32 s19, s21, s31
	s_cselect_b32 s50, s20, s30
	s_ashr_i32 s11, s10, 31
	s_lshl_b64 s[0:1], s[10:11], 19
	s_add_u32 s22, s35, s0
	s_addc_u32 s23, s36, s1
	s_and_b64 s[0:1], s[4:5], exec
	s_cselect_b32 s11, s23, s27
	s_cselect_b32 s51, s22, s26
	s_add_u32 s0, s30, 0x40080
	s_addc_u32 s1, s31, 0
	s_add_u32 s52, s26, 0x100
	v_mov_b32_e32 v0, 0
	s_addc_u32 s53, s27, 0
	s_mov_b32 s54, -2
	v_mov_b32_e32 v1, v0
	v_mov_b32_e32 v2, v0
	v_mov_b32_e32 v3, v0
	v_mov_b32_e32 v8, v0
	v_mov_b32_e32 v9, v0
	v_mov_b32_e32 v10, v0
	v_mov_b32_e32 v11, v0
	v_mov_b32_e32 v16, v0
	v_mov_b32_e32 v17, v0
	v_mov_b32_e32 v18, v0
	v_mov_b32_e32 v19, v0
	v_mov_b32_e32 v24, v0
	v_mov_b32_e32 v25, v0
	v_mov_b32_e32 v26, v0
	v_mov_b32_e32 v27, v0
	v_mov_b32_e32 v32, v0
	v_mov_b32_e32 v33, v0
	v_mov_b32_e32 v34, v0
	v_mov_b32_e32 v35, v0
	v_mov_b32_e32 v40, v0
	v_mov_b32_e32 v41, v0
	v_mov_b32_e32 v42, v0
	v_mov_b32_e32 v43, v0
	v_mov_b32_e32 v48, v0
	v_mov_b32_e32 v49, v0
	v_mov_b32_e32 v50, v0
	v_mov_b32_e32 v51, v0
	v_mov_b32_e32 v56, v0
	v_mov_b32_e32 v57, v0
	v_mov_b32_e32 v58, v0
	v_mov_b32_e32 v59, v0
	v_mov_b32_e32 v4, v0
	v_mov_b32_e32 v5, v0
	v_mov_b32_e32 v6, v0
	v_mov_b32_e32 v7, v0
	v_mov_b32_e32 v12, v0
	v_mov_b32_e32 v13, v0
	v_mov_b32_e32 v14, v0
	v_mov_b32_e32 v15, v0
	v_mov_b32_e32 v20, v0
	v_mov_b32_e32 v21, v0
	v_mov_b32_e32 v22, v0
	v_mov_b32_e32 v23, v0
	v_mov_b32_e32 v28, v0
	v_mov_b32_e32 v29, v0
	v_mov_b32_e32 v30, v0
	v_mov_b32_e32 v31, v0
	v_mov_b32_e32 v36, v0
	v_mov_b32_e32 v37, v0
	v_mov_b32_e32 v38, v0
	v_mov_b32_e32 v39, v0
	v_mov_b32_e32 v44, v0
	v_mov_b32_e32 v45, v0
	v_mov_b32_e32 v46, v0
	v_mov_b32_e32 v47, v0
	v_mov_b32_e32 v52, v0
	v_mov_b32_e32 v53, v0
	v_mov_b32_e32 v54, v0
	v_mov_b32_e32 v55, v0
	v_mov_b32_e32 v60, v0
	v_mov_b32_e32 v61, v0
	v_mov_b32_e32 v62, v0
	v_mov_b32_e32 v63, v0
	v_mov_b32_e32 v64, v0
	v_mov_b32_e32 v65, v0
	v_mov_b32_e32 v66, v0
	v_mov_b32_e32 v67, v0
	v_mov_b32_e32 v72, v0
	v_mov_b32_e32 v73, v0
	v_mov_b32_e32 v74, v0
	v_mov_b32_e32 v75, v0
	v_mov_b32_e32 v80, v0
	v_mov_b32_e32 v81, v0
	v_mov_b32_e32 v82, v0
	v_mov_b32_e32 v83, v0
	v_mov_b32_e32 v88, v0
	v_mov_b32_e32 v89, v0
	v_mov_b32_e32 v90, v0
	v_mov_b32_e32 v91, v0
	v_mov_b32_e32 v96, v0
	v_mov_b32_e32 v97, v0
	v_mov_b32_e32 v98, v0
	v_mov_b32_e32 v99, v0
	v_mov_b32_e32 v104, v0
	v_mov_b32_e32 v105, v0
	v_mov_b32_e32 v106, v0
	v_mov_b32_e32 v107, v0
	v_mov_b32_e32 v112, v0
	v_mov_b32_e32 v113, v0
	v_mov_b32_e32 v114, v0
	v_mov_b32_e32 v115, v0
	v_mov_b32_e32 v120, v0
	v_mov_b32_e32 v121, v0
	v_mov_b32_e32 v122, v0
	v_mov_b32_e32 v123, v0
	v_mov_b32_e32 v68, v0
	v_mov_b32_e32 v69, v0
	v_mov_b32_e32 v70, v0
	v_mov_b32_e32 v71, v0
	v_mov_b32_e32 v76, v0
	v_mov_b32_e32 v77, v0
	v_mov_b32_e32 v78, v0
	v_mov_b32_e32 v79, v0
	v_mov_b32_e32 v84, v0
	v_mov_b32_e32 v85, v0
	v_mov_b32_e32 v86, v0
	v_mov_b32_e32 v87, v0
	v_mov_b32_e32 v92, v0
	v_mov_b32_e32 v93, v0
	v_mov_b32_e32 v94, v0
	v_mov_b32_e32 v95, v0
	v_mov_b32_e32 v100, v0
	v_mov_b32_e32 v101, v0
	v_mov_b32_e32 v102, v0
	v_mov_b32_e32 v103, v0
	v_mov_b32_e32 v108, v0
	v_mov_b32_e32 v109, v0
	v_mov_b32_e32 v110, v0
	v_mov_b32_e32 v111, v0
	v_mov_b32_e32 v116, v0
	v_mov_b32_e32 v117, v0
	v_mov_b32_e32 v118, v0
	v_mov_b32_e32 v119, v0
	v_mov_b32_e32 v124, v0
	v_mov_b32_e32 v125, v0
	v_mov_b32_e32 v126, v0
	v_mov_b32_e32 v127, v0
	v_readfirstlane_b32 s100, v206
	s_nop 0
	s_cmp_lt_u32 s100, 0x100
	s_cbranch_scc1 .Lprio_skip_0
	s_setprio 1
.Lprio_skip_0:
	.p2alignl 6, 3212836864
.LBB0_253:
	s_add_u32 s26, s0, 0xfffc0080
	s_addc_u32 s27, s1, -1
	s_add_i32 s55, 0, 0x10000
	s_cmp_eq_u32 s54, 12
	s_cselect_b32 s31, s19, s27
	s_cselect_b32 s30, s50, s26
	v_add_u32_e32 v138, s55, v141
	s_cselect_b32 s27, s11, s53
	s_cselect_b32 s26, s51, s52
	s_add_i32 s58, 0, 0x14000
	ds_read_b128 v[144:147], v138
	ds_read_b128 v[158:161], v138 offset:1024
	ds_read_b128 v[162:165], v138 offset:2048
	ds_read_b128 v[166:169], v138 offset:3072
	v_add_u32_e32 v138, s58, v141
	ds_read_b128 v[170:173], v138
	ds_read_b128 v[174:177], v138 offset:1024
	ds_read_b128 v[178:181], v138 offset:2048
	ds_read_b128 v[182:185], v138 offset:3072
	v_lshl_add_u64 v[138:139], s[0:1], 0, v[134:135]
	s_add_i32 m0, s38, 0xc000
	ds_read_b128 v[186:189], v143
	ds_read_b128 v[190:193], v143 offset:1024
	ds_read_b128 v[194:197], v143 offset:2048
	ds_read_b128 v[198:201], v143 offset:3072
	ds_read_b128 v[202:205], v143 offset:4096
	ds_read_b128 v[218:221], v143 offset:5120
	ds_read_b128 v[222:225], v143 offset:6144
	ds_read_b128 v[226:229], v143 offset:7168
	global_load_lds_dwordx4 v[138:139], off
	v_lshl_add_u64 v[138:139], s[0:1], 0, v[136:137]
	s_add_i32 m0, s38, 0xe000
	s_nop 0
	global_load_lds_dwordx4 v[138:139], off
	s_waitcnt vmcnt(8)
	s_waitcnt lgkmcnt(0)
	s_barrier
	s_waitcnt lgkmcnt(0)
	v_mfma_f32_16x16x32_bf16 v[124:127], v[144:147], v[186:189], v[124:127]
	v_mfma_f32_16x16x32_bf16 v[116:119], v[162:165], v[186:189], v[116:119]
	v_mfma_f32_16x16x32_bf16 v[108:111], v[144:147], v[194:197], v[108:111]
	v_mfma_f32_16x16x32_bf16 v[100:103], v[162:165], v[194:197], v[100:103]
	v_mfma_f32_16x16x32_bf16 v[92:95], v[144:147], v[202:205], v[92:95]
	v_mfma_f32_16x16x32_bf16 v[84:87], v[162:165], v[202:205], v[84:87]
	v_mfma_f32_16x16x32_bf16 v[76:79], v[144:147], v[222:225], v[76:79]
	v_mfma_f32_16x16x32_bf16 v[68:71], v[162:165], v[222:225], v[68:71]
	v_mfma_f32_16x16x32_bf16 v[124:127], v[158:161], v[190:193], v[124:127]
	v_mfma_f32_16x16x32_bf16 v[116:119], v[166:169], v[190:193], v[116:119]
	v_mfma_f32_16x16x32_bf16 v[108:111], v[158:161], v[198:201], v[108:111]
	v_mfma_f32_16x16x32_bf16 v[100:103], v[166:169], v[198:201], v[100:103]
	v_mfma_f32_16x16x32_bf16 v[92:95], v[158:161], v[218:221], v[92:95]
	v_mfma_f32_16x16x32_bf16 v[84:87], v[166:169], v[218:221], v[84:87]
	v_mfma_f32_16x16x32_bf16 v[76:79], v[158:161], v[226:229], v[76:79]
	v_mfma_f32_16x16x32_bf16 v[68:71], v[166:169], v[226:229], v[68:71]
	v_mfma_f32_16x16x32_bf16 v[120:123], v[170:173], v[186:189], v[120:123]
	v_mfma_f32_16x16x32_bf16 v[112:115], v[178:181], v[186:189], v[112:115]
	v_mfma_f32_16x16x32_bf16 v[104:107], v[170:173], v[194:197], v[104:107]
	v_mfma_f32_16x16x32_bf16 v[96:99], v[178:181], v[194:197], v[96:99]
	v_mfma_f32_16x16x32_bf16 v[88:91], v[170:173], v[202:205], v[88:91]
	v_mfma_f32_16x16x32_bf16 v[80:83], v[178:181], v[202:205], v[80:83]
	v_mfma_f32_16x16x32_bf16 v[72:75], v[170:173], v[222:225], v[72:75]
	v_mfma_f32_16x16x32_bf16 v[64:67], v[178:181], v[222:225], v[64:67]
	v_mfma_f32_16x16x32_bf16 v[120:123], v[174:177], v[190:193], v[120:123]
	v_mfma_f32_16x16x32_bf16 v[112:115], v[182:185], v[190:193], v[112:115]
	v_mfma_f32_16x16x32_bf16 v[104:107], v[174:177], v[198:201], v[104:107]
	v_mfma_f32_16x16x32_bf16 v[96:99], v[182:185], v[198:201], v[96:99]
	v_mfma_f32_16x16x32_bf16 v[88:91], v[174:177], v[218:221], v[88:91]
	v_mfma_f32_16x16x32_bf16 v[80:83], v[182:185], v[218:221], v[80:83]
	v_mfma_f32_16x16x32_bf16 v[72:75], v[174:177], v[226:229], v[72:75]
	v_mfma_f32_16x16x32_bf16 v[64:67], v[182:185], v[226:229], v[64:67]
	s_barrier
	s_add_i32 s55, s55, s37
	v_lshl_add_u64 v[138:139], s[26:27], 0, v[148:149]
	s_mov_b32 m0, s55
	ds_read_b128 v[186:189], v143 offset:16384
	ds_read_b128 v[190:193], v143 offset:17408
	ds_read_b128 v[194:197], v143 offset:18432
	ds_read_b128 v[198:201], v143 offset:19456
	ds_read_b128 v[202:205], v143 offset:20480
	ds_read_b128 v[218:221], v143 offset:21504
	ds_read_b128 v[222:225], v143 offset:22528
	ds_read_b128 v[226:229], v143 offset:23552
	global_load_lds_dwordx4 v[138:139], off
	s_add_i32 m0, s55, 0x2000
	s_add_u32 s56, s26, 0x40000
	v_lshl_add_u64 v[154:155], s[26:27], 0, v[128:129]
	s_addc_u32 s57, s27, 0
	s_add_i32 s55, s58, s37
	global_load_lds_dwordx4 v[154:155], off
	v_lshl_add_u64 v[156:157], s[56:57], 0, v[148:149]
	s_mov_b32 m0, s55
	v_lshl_add_u64 v[212:213], s[30:31], 0, v[130:131]
	global_load_lds_dwordx4 v[156:157], off
	v_lshl_add_u64 v[156:157], s[56:57], 0, v[128:129]
	s_add_i32 m0, s55, 0x2000
	s_nop 0
	global_load_lds_dwordx4 v[156:157], off
	v_lshl_add_u64 v[156:157], s[30:31], 0, v[132:133]
	s_mov_b32 m0, s38
	s_nop 0
	global_load_lds_dwordx4 v[156:157], off
	s_mov_b32 m0, s39
	s_nop 0
	global_load_lds_dwordx4 v[212:213], off
	s_waitcnt vmcnt(8)
	s_waitcnt lgkmcnt(0)
	s_barrier
	s_waitcnt lgkmcnt(0)
	v_mfma_f32_16x16x32_bf16 v[60:63], v[144:147], v[186:189], v[60:63]
	v_mfma_f32_16x16x32_bf16 v[52:55], v[162:165], v[186:189], v[52:55]
	v_mfma_f32_16x16x32_bf16 v[44:47], v[144:147], v[194:197], v[44:47]
	v_mfma_f32_16x16x32_bf16 v[36:39], v[162:165], v[194:197], v[36:39]
	v_mfma_f32_16x16x32_bf16 v[28:31], v[144:147], v[202:205], v[28:31]
	v_mfma_f32_16x16x32_bf16 v[20:23], v[162:165], v[202:205], v[20:23]
	v_mfma_f32_16x16x32_bf16 v[12:15], v[144:147], v[222:225], v[12:15]
	v_mfma_f32_16x16x32_bf16 v[4:7], v[162:165], v[222:225], v[4:7]
	v_mfma_f32_16x16x32_bf16 v[60:63], v[158:161], v[190:193], v[60:63]
	v_mfma_f32_16x16x32_bf16 v[52:55], v[166:169], v[190:193], v[52:55]
	v_mfma_f32_16x16x32_bf16 v[44:47], v[158:161], v[198:201], v[44:47]
	v_mfma_f32_16x16x32_bf16 v[36:39], v[166:169], v[198:201], v[36:39]
	v_mfma_f32_16x16x32_bf16 v[28:31], v[158:161], v[218:221], v[28:31]
	v_mfma_f32_16x16x32_bf16 v[20:23], v[166:169], v[218:221], v[20:23]
	v_mfma_f32_16x16x32_bf16 v[12:15], v[158:161], v[226:229], v[12:15]
	v_mfma_f32_16x16x32_bf16 v[4:7], v[166:169], v[226:229], v[4:7]
	v_mfma_f32_16x16x32_bf16 v[56:59], v[170:173], v[186:189], v[56:59]
	v_mfma_f32_16x16x32_bf16 v[48:51], v[178:181], v[186:189], v[48:51]
	v_mfma_f32_16x16x32_bf16 v[40:43], v[170:173], v[194:197], v[40:43]
	v_mfma_f32_16x16x32_bf16 v[32:35], v[178:181], v[194:197], v[32:35]
	v_mfma_f32_16x16x32_bf16 v[24:27], v[170:173], v[202:205], v[24:27]
	v_mfma_f32_16x16x32_bf16 v[16:19], v[178:181], v[202:205], v[16:19]
	v_mfma_f32_16x16x32_bf16 v[8:11], v[170:173], v[222:225], v[8:11]
	v_mfma_f32_16x16x32_bf16 v[0:3], v[178:181], v[222:225], v[0:3]
	v_mfma_f32_16x16x32_bf16 v[56:59], v[174:177], v[190:193], v[56:59]
	v_mfma_f32_16x16x32_bf16 v[48:51], v[182:185], v[190:193], v[48:51]
	v_mfma_f32_16x16x32_bf16 v[40:43], v[174:177], v[198:201], v[40:43]
	v_mfma_f32_16x16x32_bf16 v[32:35], v[182:185], v[198:201], v[32:35]
	v_mfma_f32_16x16x32_bf16 v[24:27], v[174:177], v[218:221], v[24:27]
	v_mfma_f32_16x16x32_bf16 v[16:19], v[182:185], v[218:221], v[16:19]
	v_mfma_f32_16x16x32_bf16 v[8:11], v[174:177], v[226:229], v[8:11]
	v_mfma_f32_16x16x32_bf16 v[0:3], v[182:185], v[226:229], v[0:3]
	s_barrier
	s_add_i32 s55, 0, 0x18000
	v_add_u32_e32 v140, s55, v141
	s_add_i32 s56, 0, 0x1c000
	ds_read_b128 v[144:147], v140
	ds_read_b128 v[158:161], v140 offset:1024
	ds_read_b128 v[162:165], v140 offset:2048
	ds_read_b128 v[166:169], v140 offset:3072
	v_add_u32_e32 v140, s56, v141
	ds_read_b128 v[170:173], v140
	ds_read_b128 v[174:177], v140 offset:1024
	ds_read_b128 v[178:181], v140 offset:2048
	ds_read_b128 v[182:185], v140 offset:3072
	s_add_u32 s30, s30, 0x40000
	s_addc_u32 s31, s31, 0
	s_mov_b32 m0, s40
	v_lshl_add_u64 v[214:215], s[30:31], 0, v[132:133]
	ds_read_b128 v[186:189], v143 offset:32768
	ds_read_b128 v[190:193], v143 offset:33792
	ds_read_b128 v[194:197], v143 offset:34816
	ds_read_b128 v[198:201], v143 offset:35840
	ds_read_b128 v[202:205], v143 offset:36864
	ds_read_b128 v[218:221], v143 offset:37888
	ds_read_b128 v[222:225], v143 offset:38912
	ds_read_b128 v[226:229], v143 offset:39936
	global_load_lds_dwordx4 v[214:215], off
	v_lshl_add_u64 v[214:215], s[30:31], 0, v[130:131]
	s_mov_b32 m0, s41
	s_nop 0
	global_load_lds_dwordx4 v[214:215], off
	s_waitcnt vmcnt(8)
	s_waitcnt lgkmcnt(0)
	s_barrier
	s_waitcnt lgkmcnt(0)
	v_mfma_f32_16x16x32_bf16 v[124:127], v[144:147], v[186:189], v[124:127]
	v_mfma_f32_16x16x32_bf16 v[116:119], v[162:165], v[186:189], v[116:119]
	v_mfma_f32_16x16x32_bf16 v[108:111], v[144:147], v[194:197], v[108:111]
	v_mfma_f32_16x16x32_bf16 v[100:103], v[162:165], v[194:197], v[100:103]
	v_mfma_f32_16x16x32_bf16 v[92:95], v[144:147], v[202:205], v[92:95]
	v_mfma_f32_16x16x32_bf16 v[84:87], v[162:165], v[202:205], v[84:87]
	v_mfma_f32_16x16x32_bf16 v[76:79], v[144:147], v[222:225], v[76:79]
	v_mfma_f32_16x16x32_bf16 v[68:71], v[162:165], v[222:225], v[68:71]
	v_mfma_f32_16x16x32_bf16 v[124:127], v[158:161], v[190:193], v[124:127]
	v_mfma_f32_16x16x32_bf16 v[116:119], v[166:169], v[190:193], v[116:119]
	v_mfma_f32_16x16x32_bf16 v[108:111], v[158:161], v[198:201], v[108:111]
	v_mfma_f32_16x16x32_bf16 v[100:103], v[166:169], v[198:201], v[100:103]
	v_mfma_f32_16x16x32_bf16 v[92:95], v[158:161], v[218:221], v[92:95]
	v_mfma_f32_16x16x32_bf16 v[84:87], v[166:169], v[218:221], v[84:87]
	v_mfma_f32_16x16x32_bf16 v[76:79], v[158:161], v[226:229], v[76:79]
	v_mfma_f32_16x16x32_bf16 v[68:71], v[166:169], v[226:229], v[68:71]
	v_mfma_f32_16x16x32_bf16 v[120:123], v[170:173], v[186:189], v[120:123]
	v_mfma_f32_16x16x32_bf16 v[112:115], v[178:181], v[186:189], v[112:115]
	v_mfma_f32_16x16x32_bf16 v[104:107], v[170:173], v[194:197], v[104:107]
	v_mfma_f32_16x16x32_bf16 v[96:99], v[178:181], v[194:197], v[96:99]
	v_mfma_f32_16x16x32_bf16 v[88:91], v[170:173], v[202:205], v[88:91]
	v_mfma_f32_16x16x32_bf16 v[80:83], v[178:181], v[202:205], v[80:83]
	v_mfma_f32_16x16x32_bf16 v[72:75], v[170:173], v[222:225], v[72:75]
	v_mfma_f32_16x16x32_bf16 v[64:67], v[178:181], v[222:225], v[64:67]
	v_mfma_f32_16x16x32_bf16 v[120:123], v[174:177], v[190:193], v[120:123]
	v_mfma_f32_16x16x32_bf16 v[112:115], v[182:185], v[190:193], v[112:115]
	v_mfma_f32_16x16x32_bf16 v[104:107], v[174:177], v[198:201], v[104:107]
	v_mfma_f32_16x16x32_bf16 v[96:99], v[182:185], v[198:201], v[96:99]
	v_mfma_f32_16x16x32_bf16 v[88:91], v[174:177], v[218:221], v[88:91]
	v_mfma_f32_16x16x32_bf16 v[80:83], v[182:185], v[218:221], v[80:83]
	v_mfma_f32_16x16x32_bf16 v[72:75], v[174:177], v[226:229], v[72:75]
	v_mfma_f32_16x16x32_bf16 v[64:67], v[182:185], v[226:229], v[64:67]
	s_barrier
	s_add_i32 s30, s55, s37
	v_lshl_add_u64 v[138:139], v[138:139], 0, s[28:29]
	s_mov_b32 m0, s30
	ds_read_b128 v[186:189], v143 offset:49152
	ds_read_b128 v[190:193], v143 offset:50176
	ds_read_b128 v[194:197], v143 offset:51200
	ds_read_b128 v[198:201], v143 offset:52224
	ds_read_b128 v[202:205], v143 offset:53248
	ds_read_b128 v[218:221], v143 offset:54272
	ds_read_b128 v[222:225], v143 offset:55296
	ds_read_b128 v[226:229], v143 offset:56320
	global_load_lds_dwordx4 v[138:139], off
	s_add_i32 m0, s30, 0x2000
	s_add_u32 s26, s26, 0x40080
	v_lshl_add_u64 v[138:139], v[154:155], 0, s[28:29]
	s_addc_u32 s27, s27, 0
	s_add_i32 s30, s56, s37
	global_load_lds_dwordx4 v[138:139], off
	v_lshl_add_u64 v[138:139], s[26:27], 0, v[148:149]
	s_mov_b32 m0, s30
	s_nop 0
	global_load_lds_dwordx4 v[138:139], off
	v_lshl_add_u64 v[138:139], s[26:27], 0, v[128:129]
	s_add_i32 m0, s30, 0x2000
	s_nop 0
	global_load_lds_dwordx4 v[138:139], off
	v_lshl_add_u64 v[138:139], v[156:157], 0, s[28:29]
	s_mov_b32 m0, s46
	s_nop 0
	global_load_lds_dwordx4 v[138:139], off
	v_lshl_add_u64 v[138:139], v[212:213], 0, s[28:29]
	s_mov_b32 m0, s47
	s_nop 0
	global_load_lds_dwordx4 v[138:139], off
	s_waitcnt vmcnt(8)
	s_waitcnt lgkmcnt(0)
	s_barrier
	s_waitcnt lgkmcnt(0)
	v_mfma_f32_16x16x32_bf16 v[60:63], v[144:147], v[186:189], v[60:63]
	v_mfma_f32_16x16x32_bf16 v[52:55], v[162:165], v[186:189], v[52:55]
	v_mfma_f32_16x16x32_bf16 v[44:47], v[144:147], v[194:197], v[44:47]
	v_mfma_f32_16x16x32_bf16 v[36:39], v[162:165], v[194:197], v[36:39]
	v_mfma_f32_16x16x32_bf16 v[28:31], v[144:147], v[202:205], v[28:31]
	v_mfma_f32_16x16x32_bf16 v[20:23], v[162:165], v[202:205], v[20:23]
	v_mfma_f32_16x16x32_bf16 v[12:15], v[144:147], v[222:225], v[12:15]
	v_mfma_f32_16x16x32_bf16 v[4:7], v[162:165], v[222:225], v[4:7]
	v_mfma_f32_16x16x32_bf16 v[60:63], v[158:161], v[190:193], v[60:63]
	v_mfma_f32_16x16x32_bf16 v[52:55], v[166:169], v[190:193], v[52:55]
	v_mfma_f32_16x16x32_bf16 v[44:47], v[158:161], v[198:201], v[44:47]
	v_mfma_f32_16x16x32_bf16 v[36:39], v[166:169], v[198:201], v[36:39]
	v_mfma_f32_16x16x32_bf16 v[28:31], v[158:161], v[218:221], v[28:31]
	v_mfma_f32_16x16x32_bf16 v[20:23], v[166:169], v[218:221], v[20:23]
	v_mfma_f32_16x16x32_bf16 v[12:15], v[158:161], v[226:229], v[12:15]
	v_mfma_f32_16x16x32_bf16 v[4:7], v[166:169], v[226:229], v[4:7]
	v_mfma_f32_16x16x32_bf16 v[56:59], v[170:173], v[186:189], v[56:59]
	v_mfma_f32_16x16x32_bf16 v[48:51], v[178:181], v[186:189], v[48:51]
	v_mfma_f32_16x16x32_bf16 v[40:43], v[170:173], v[194:197], v[40:43]
	v_mfma_f32_16x16x32_bf16 v[32:35], v[178:181], v[194:197], v[32:35]
	v_mfma_f32_16x16x32_bf16 v[24:27], v[170:173], v[202:205], v[24:27]
	v_mfma_f32_16x16x32_bf16 v[16:19], v[178:181], v[202:205], v[16:19]
	v_mfma_f32_16x16x32_bf16 v[8:11], v[170:173], v[222:225], v[8:11]
	v_mfma_f32_16x16x32_bf16 v[0:3], v[178:181], v[222:225], v[0:3]
	v_mfma_f32_16x16x32_bf16 v[56:59], v[174:177], v[190:193], v[56:59]
	v_mfma_f32_16x16x32_bf16 v[48:51], v[182:185], v[190:193], v[48:51]
	v_mfma_f32_16x16x32_bf16 v[40:43], v[174:177], v[198:201], v[40:43]
	v_mfma_f32_16x16x32_bf16 v[32:35], v[182:185], v[198:201], v[32:35]
	v_mfma_f32_16x16x32_bf16 v[24:27], v[174:177], v[218:221], v[24:27]
	v_mfma_f32_16x16x32_bf16 v[16:19], v[182:185], v[218:221], v[16:19]
	v_mfma_f32_16x16x32_bf16 v[8:11], v[174:177], v[226:229], v[8:11]
	v_mfma_f32_16x16x32_bf16 v[0:3], v[182:185], v[226:229], v[0:3]
	s_barrier
	s_add_i32 s54, s54, 2
	s_add_u32 s0, s0, 0x100
	s_addc_u32 s1, s1, 0
	s_add_u32 s52, s52, 0x100
	s_addc_u32 s53, s53, 0
	s_cmp_gt_u32 s54, 13
	s_cbranch_scc0 .LBB0_253
	s_setprio 0
	s_and_b64 vcc, exec, s[8:9]
	s_cbranch_vccz .LBB0_256
	s_barrier

.LBB0_359:
	s_add_u32 s42, s8, 0x100
	v_mov_b32_e32 v0, 0
	s_addc_u32 s43, s9, 0
	s_mov_b32 s44, -2
	v_mov_b32_e32 v1, v0
	v_mov_b32_e32 v2, v0
	v_mov_b32_e32 v3, v0
	v_mov_b32_e32 v4, v0
	v_mov_b32_e32 v5, v0
	v_mov_b32_e32 v6, v0
	v_mov_b32_e32 v7, v0
	v_mov_b32_e32 v16, v0
	v_mov_b32_e32 v17, v0
	v_mov_b32_e32 v18, v0
	v_mov_b32_e32 v19, v0
	v_mov_b32_e32 v20, v0
	v_mov_b32_e32 v21, v0
	v_mov_b32_e32 v22, v0
	v_mov_b32_e32 v23, v0
	v_mov_b32_e32 v32, v0
	v_mov_b32_e32 v33, v0
	v_mov_b32_e32 v34, v0
	v_mov_b32_e32 v35, v0
	v_mov_b32_e32 v36, v0
	v_mov_b32_e32 v37, v0
	v_mov_b32_e32 v38, v0
	v_mov_b32_e32 v39, v0
	v_mov_b32_e32 v48, v0
	v_mov_b32_e32 v49, v0
	v_mov_b32_e32 v50, v0
	v_mov_b32_e32 v51, v0
	v_mov_b32_e32 v52, v0
	v_mov_b32_e32 v53, v0
	v_mov_b32_e32 v54, v0
	v_mov_b32_e32 v55, v0
	v_mov_b32_e32 v8, v0
	v_mov_b32_e32 v9, v0
	v_mov_b32_e32 v10, v0
	v_mov_b32_e32 v11, v0
	v_mov_b32_e32 v12, v0
	v_mov_b32_e32 v13, v0
	v_mov_b32_e32 v14, v0
	v_mov_b32_e32 v15, v0
	v_mov_b32_e32 v24, v0
	v_mov_b32_e32 v25, v0
	v_mov_b32_e32 v26, v0
	v_mov_b32_e32 v27, v0
	v_mov_b32_e32 v28, v0
	v_mov_b32_e32 v29, v0
	v_mov_b32_e32 v30, v0
	v_mov_b32_e32 v31, v0
	v_mov_b32_e32 v40, v0
	v_mov_b32_e32 v41, v0
	v_mov_b32_e32 v42, v0
	v_mov_b32_e32 v43, v0
	v_mov_b32_e32 v44, v0
	v_mov_b32_e32 v45, v0
	v_mov_b32_e32 v46, v0
	v_mov_b32_e32 v47, v0
	v_mov_b32_e32 v56, v0
	v_mov_b32_e32 v57, v0
	v_mov_b32_e32 v58, v0
	v_mov_b32_e32 v59, v0
	v_mov_b32_e32 v60, v0
	v_mov_b32_e32 v61, v0
	v_mov_b32_e32 v62, v0
	v_mov_b32_e32 v63, v0
	v_mov_b32_e32 v64, v0
	v_mov_b32_e32 v65, v0
	v_mov_b32_e32 v66, v0
	v_mov_b32_e32 v67, v0
	v_mov_b32_e32 v68, v0
	v_mov_b32_e32 v69, v0
	v_mov_b32_e32 v70, v0
	v_mov_b32_e32 v71, v0
	v_mov_b32_e32 v80, v0
	v_mov_b32_e32 v81, v0
	v_mov_b32_e32 v82, v0
	v_mov_b32_e32 v83, v0
	v_mov_b32_e32 v84, v0
	v_mov_b32_e32 v85, v0
	v_mov_b32_e32 v86, v0
	v_mov_b32_e32 v87, v0
	v_mov_b32_e32 v96, v0
	v_mov_b32_e32 v97, v0
	v_mov_b32_e32 v98, v0
	v_mov_b32_e32 v99, v0
	v_mov_b32_e32 v100, v0
	v_mov_b32_e32 v101, v0
	v_mov_b32_e32 v102, v0
	v_mov_b32_e32 v103, v0
	v_mov_b32_e32 v112, v0
	v_mov_b32_e32 v113, v0
	v_mov_b32_e32 v114, v0
	v_mov_b32_e32 v115, v0
	v_mov_b32_e32 v116, v0
	v_mov_b32_e32 v117, v0
	v_mov_b32_e32 v118, v0
	v_mov_b32_e32 v119, v0
	v_mov_b32_e32 v72, v0
	v_mov_b32_e32 v73, v0
	v_mov_b32_e32 v74, v0
	v_mov_b32_e32 v75, v0
	v_mov_b32_e32 v76, v0
	v_mov_b32_e32 v77, v0
	v_mov_b32_e32 v78, v0
	v_mov_b32_e32 v79, v0
	v_mov_b32_e32 v88, v0
	v_mov_b32_e32 v89, v0
	v_mov_b32_e32 v90, v0
	v_mov_b32_e32 v91, v0
	v_mov_b32_e32 v92, v0
	v_mov_b32_e32 v93, v0
	v_mov_b32_e32 v94, v0
	v_mov_b32_e32 v95, v0
	v_mov_b32_e32 v104, v0
	v_mov_b32_e32 v105, v0
	v_mov_b32_e32 v106, v0
	v_mov_b32_e32 v107, v0
	v_mov_b32_e32 v108, v0
	v_mov_b32_e32 v109, v0
	v_mov_b32_e32 v110, v0
	v_mov_b32_e32 v111, v0
	v_mov_b32_e32 v120, v0
	v_mov_b32_e32 v121, v0
	v_mov_b32_e32 v122, v0
	v_mov_b32_e32 v123, v0
	v_mov_b32_e32 v124, v0
	v_mov_b32_e32 v125, v0
	v_mov_b32_e32 v126, v0
	v_mov_b32_e32 v127, v0
	v_readfirstlane_b32 s100, v206
	s_nop 0
	s_cmp_lt_u32 s100, 0x100
	s_cbranch_scc1 .Lprio_skip_1
	s_setprio 1

.LBB0_360:
	s_add_u32 s0, s4, 0x100
	s_addc_u32 s1, s5, 0
	s_add_i32 s45, 0, 0x10000
	s_cmp_eq_u32 s44, 40
	s_cselect_b32 s9, s39, s1
	s_cselect_b32 s8, s38, s0
	v_add_u32_e32 v146, s45, v168
	s_cselect_b32 s3, s41, s43
	s_cselect_b32 s2, s40, s42
	s_add_i32 s62, 0, 0x14000
	ds_read_b128 v[128:131], v146
	ds_read_b128 v[132:135], v146 offset:1024
	ds_read_b128 v[158:161], v146 offset:2048
	ds_read_b128 v[162:165], v146 offset:3072
	v_add_u32_e32 v146, s62, v168
	ds_read_b128 v[170:173], v146
	ds_read_b128 v[174:177], v146 offset:1024
	ds_read_b128 v[178:181], v146 offset:2048
	ds_read_b128 v[182:185], v146 offset:3072
	v_lshl_add_u64 v[146:147], s[4:5], 0, v[142:143]
	s_add_i32 m0, s50, 0xc000
	ds_read_b128 v[186:189], v169
	ds_read_b128 v[190:193], v169 offset:1024
	ds_read_b128 v[194:197], v169 offset:2048
	ds_read_b128 v[198:201], v169 offset:3072
	ds_read_b128 v[202:205], v169 offset:4096
	ds_read_b128 v[218:221], v169 offset:5120
	ds_read_b128 v[222:225], v169 offset:6144
	ds_read_b128 v[226:229], v169 offset:7168
	global_load_lds_dwordx4 v[146:147], off
	v_lshl_add_u64 v[146:147], s[4:5], 0, v[144:145]
	s_add_i32 m0, s50, 0xe000
	s_nop 0
	global_load_lds_dwordx4 v[146:147], off
	s_waitcnt vmcnt(8)
	s_waitcnt lgkmcnt(0)
	s_barrier
	s_waitcnt lgkmcnt(0)
	v_mfma_f32_16x16x32_bf16 v[124:127], v[128:131], v[186:189], v[124:127]
	v_mfma_f32_16x16x32_bf16 v[120:123], v[158:161], v[186:189], v[120:123]
	v_mfma_f32_16x16x32_bf16 v[108:111], v[128:131], v[194:197], v[108:111]
	v_mfma_f32_16x16x32_bf16 v[104:107], v[158:161], v[194:197], v[104:107]
	v_mfma_f32_16x16x32_bf16 v[92:95], v[128:131], v[202:205], v[92:95]
	v_mfma_f32_16x16x32_bf16 v[88:91], v[158:161], v[202:205], v[88:91]
	v_mfma_f32_16x16x32_bf16 v[76:79], v[128:131], v[222:225], v[76:79]
	v_mfma_f32_16x16x32_bf16 v[72:75], v[158:161], v[222:225], v[72:75]
	v_mfma_f32_16x16x32_bf16 v[124:127], v[132:135], v[190:193], v[124:127]
	v_mfma_f32_16x16x32_bf16 v[120:123], v[162:165], v[190:193], v[120:123]
	v_mfma_f32_16x16x32_bf16 v[108:111], v[132:135], v[198:201], v[108:111]
	v_mfma_f32_16x16x32_bf16 v[104:107], v[162:165], v[198:201], v[104:107]
	v_mfma_f32_16x16x32_bf16 v[92:95], v[132:135], v[218:221], v[92:95]
	v_mfma_f32_16x16x32_bf16 v[88:91], v[162:165], v[218:221], v[88:91]
	v_mfma_f32_16x16x32_bf16 v[76:79], v[132:135], v[226:229], v[76:79]
	v_mfma_f32_16x16x32_bf16 v[72:75], v[162:165], v[226:229], v[72:75]
	v_mfma_f32_16x16x32_bf16 v[116:119], v[170:173], v[186:189], v[116:119]
	v_mfma_f32_16x16x32_bf16 v[112:115], v[178:181], v[186:189], v[112:115]
	v_mfma_f32_16x16x32_bf16 v[100:103], v[170:173], v[194:197], v[100:103]
	v_mfma_f32_16x16x32_bf16 v[96:99], v[178:181], v[194:197], v[96:99]
	v_mfma_f32_16x16x32_bf16 v[84:87], v[170:173], v[202:205], v[84:87]
	v_mfma_f32_16x16x32_bf16 v[80:83], v[178:181], v[202:205], v[80:83]
	v_mfma_f32_16x16x32_bf16 v[68:71], v[170:173], v[222:225], v[68:71]
	v_mfma_f32_16x16x32_bf16 v[64:67], v[178:181], v[222:225], v[64:67]
	v_mfma_f32_16x16x32_bf16 v[116:119], v[174:177], v[190:193], v[116:119]
	v_mfma_f32_16x16x32_bf16 v[112:115], v[182:185], v[190:193], v[112:115]
	v_mfma_f32_16x16x32_bf16 v[100:103], v[174:177], v[198:201], v[100:103]
	v_mfma_f32_16x16x32_bf16 v[96:99], v[182:185], v[198:201], v[96:99]
	v_mfma_f32_16x16x32_bf16 v[84:87], v[174:177], v[218:221], v[84:87]
	v_mfma_f32_16x16x32_bf16 v[80:83], v[182:185], v[218:221], v[80:83]
	v_mfma_f32_16x16x32_bf16 v[68:71], v[174:177], v[226:229], v[68:71]
	v_mfma_f32_16x16x32_bf16 v[64:67], v[182:185], v[226:229], v[64:67]
	s_barrier
	s_add_i32 s4, s45, s49
	v_lshl_add_u64 v[146:147], s[2:3], 0, v[148:149]
	s_mov_b32 m0, s4
	ds_read_b128 v[186:189], v169 offset:16384
	ds_read_b128 v[190:193], v169 offset:17408
	ds_read_b128 v[194:197], v169 offset:18432
	ds_read_b128 v[198:201], v169 offset:19456
	ds_read_b128 v[202:205], v169 offset:20480
	ds_read_b128 v[218:221], v169 offset:21504
	ds_read_b128 v[222:225], v169 offset:22528
	ds_read_b128 v[226:229], v169 offset:23552
	global_load_lds_dwordx4 v[146:147], off
	s_add_i32 m0, s4, 0x2000
	s_add_u32 s4, s2, 0xb0000
	v_lshl_add_u64 v[154:155], s[2:3], 0, v[136:137]
	s_addc_u32 s5, s3, 0
	s_add_i32 s45, s62, s49
	global_load_lds_dwordx4 v[154:155], off
	v_lshl_add_u64 v[156:157], s[4:5], 0, v[148:149]
	s_mov_b32 m0, s45
	v_lshl_add_u64 v[166:167], s[8:9], 0, v[138:139]
	global_load_lds_dwordx4 v[156:157], off
	v_lshl_add_u64 v[156:157], s[4:5], 0, v[136:137]
	s_add_i32 m0, s45, 0x2000
	s_nop 0
	global_load_lds_dwordx4 v[156:157], off
	v_lshl_add_u64 v[156:157], s[8:9], 0, v[140:141]
	s_mov_b32 m0, s50
	s_nop 0
	global_load_lds_dwordx4 v[156:157], off
	s_mov_b32 m0, s51
	s_nop 0
	global_load_lds_dwordx4 v[166:167], off
	s_waitcnt vmcnt(8)
	s_waitcnt lgkmcnt(0)
	s_barrier
	s_waitcnt lgkmcnt(0)
	v_mfma_f32_16x16x32_bf16 v[60:63], v[128:131], v[186:189], v[60:63]
	v_mfma_f32_16x16x32_bf16 v[56:59], v[158:161], v[186:189], v[56:59]
	v_mfma_f32_16x16x32_bf16 v[44:47], v[128:131], v[194:197], v[44:47]
	v_mfma_f32_16x16x32_bf16 v[40:43], v[158:161], v[194:197], v[40:43]
	v_mfma_f32_16x16x32_bf16 v[28:31], v[128:131], v[202:205], v[28:31]
	v_mfma_f32_16x16x32_bf16 v[24:27], v[158:161], v[202:205], v[24:27]
	v_mfma_f32_16x16x32_bf16 v[12:15], v[128:131], v[222:225], v[12:15]
	v_mfma_f32_16x16x32_bf16 v[8:11], v[158:161], v[222:225], v[8:11]
	v_mfma_f32_16x16x32_bf16 v[60:63], v[132:135], v[190:193], v[60:63]
	v_mfma_f32_16x16x32_bf16 v[56:59], v[162:165], v[190:193], v[56:59]
	v_mfma_f32_16x16x32_bf16 v[44:47], v[132:135], v[198:201], v[44:47]
	v_mfma_f32_16x16x32_bf16 v[40:43], v[162:165], v[198:201], v[40:43]
	v_mfma_f32_16x16x32_bf16 v[28:31], v[132:135], v[218:221], v[28:31]
	v_mfma_f32_16x16x32_bf16 v[24:27], v[162:165], v[218:221], v[24:27]
	v_mfma_f32_16x16x32_bf16 v[12:15], v[132:135], v[226:229], v[12:15]
	v_mfma_f32_16x16x32_bf16 v[8:11], v[162:165], v[226:229], v[8:11]
	v_mfma_f32_16x16x32_bf16 v[52:55], v[170:173], v[186:189], v[52:55]
	v_mfma_f32_16x16x32_bf16 v[48:51], v[178:181], v[186:189], v[48:51]
	v_mfma_f32_16x16x32_bf16 v[36:39], v[170:173], v[194:197], v[36:39]
	v_mfma_f32_16x16x32_bf16 v[32:35], v[178:181], v[194:197], v[32:35]
	v_mfma_f32_16x16x32_bf16 v[20:23], v[170:173], v[202:205], v[20:23]
	v_mfma_f32_16x16x32_bf16 v[16:19], v[178:181], v[202:205], v[16:19]
	v_mfma_f32_16x16x32_bf16 v[4:7], v[170:173], v[222:225], v[4:7]
	v_mfma_f32_16x16x32_bf16 v[0:3], v[178:181], v[222:225], v[0:3]
	v_mfma_f32_16x16x32_bf16 v[52:55], v[174:177], v[190:193], v[52:55]
	v_mfma_f32_16x16x32_bf16 v[48:51], v[182:185], v[190:193], v[48:51]
	v_mfma_f32_16x16x32_bf16 v[36:39], v[174:177], v[198:201], v[36:39]
	v_mfma_f32_16x16x32_bf16 v[32:35], v[182:185], v[198:201], v[32:35]
	v_mfma_f32_16x16x32_bf16 v[20:23], v[174:177], v[218:221], v[20:23]
	v_mfma_f32_16x16x32_bf16 v[16:19], v[182:185], v[218:221], v[16:19]
	v_mfma_f32_16x16x32_bf16 v[4:7], v[174:177], v[226:229], v[4:7]
	v_mfma_f32_16x16x32_bf16 v[0:3], v[182:185], v[226:229], v[0:3]
	s_barrier
	s_add_i32 s45, 0, 0x18000
	v_add_u32_e32 v150, s45, v168
	s_add_i32 s62, 0, 0x1c000
	ds_read_b128 v[128:131], v150
	ds_read_b128 v[132:135], v150 offset:1024
	ds_read_b128 v[158:161], v150 offset:2048
	ds_read_b128 v[162:165], v150 offset:3072
	v_add_u32_e32 v150, s62, v168
	ds_read_b128 v[170:173], v150
	ds_read_b128 v[174:177], v150 offset:1024
	ds_read_b128 v[178:181], v150 offset:2048
	ds_read_b128 v[182:185], v150 offset:3072
	s_add_u32 s4, s8, 0xb0000
	s_addc_u32 s5, s9, 0
	s_mov_b32 m0, s52
	v_lshl_add_u64 v[212:213], s[4:5], 0, v[140:141]
	ds_read_b128 v[186:189], v169 offset:32768
	ds_read_b128 v[190:193], v169 offset:33792
	ds_read_b128 v[194:197], v169 offset:34816
	ds_read_b128 v[198:201], v169 offset:35840
	ds_read_b128 v[202:205], v169 offset:36864
	ds_read_b128 v[218:221], v169 offset:37888
	ds_read_b128 v[222:225], v169 offset:38912
	ds_read_b128 v[226:229], v169 offset:39936
	global_load_lds_dwordx4 v[212:213], off
	v_lshl_add_u64 v[212:213], s[4:5], 0, v[138:139]
	s_mov_b32 m0, s53
	s_nop 0
	global_load_lds_dwordx4 v[212:213], off
	s_waitcnt vmcnt(8)
	s_waitcnt lgkmcnt(0)
	s_barrier
	s_waitcnt lgkmcnt(0)
	v_mfma_f32_16x16x32_bf16 v[124:127], v[128:131], v[186:189], v[124:127]
	v_mfma_f32_16x16x32_bf16 v[120:123], v[158:161], v[186:189], v[120:123]
	v_mfma_f32_16x16x32_bf16 v[108:111], v[128:131], v[194:197], v[108:111]
	v_mfma_f32_16x16x32_bf16 v[104:107], v[158:161], v[194:197], v[104:107]
	v_mfma_f32_16x16x32_bf16 v[92:95], v[128:131], v[202:205], v[92:95]
	v_mfma_f32_16x16x32_bf16 v[88:91], v[158:161], v[202:205], v[88:91]
	v_mfma_f32_16x16x32_bf16 v[76:79], v[128:131], v[222:225], v[76:79]
	v_mfma_f32_16x16x32_bf16 v[72:75], v[158:161], v[222:225], v[72:75]
	v_mfma_f32_16x16x32_bf16 v[124:127], v[132:135], v[190:193], v[124:127]
	v_mfma_f32_16x16x32_bf16 v[120:123], v[162:165], v[190:193], v[120:123]
	v_mfma_f32_16x16x32_bf16 v[108:111], v[132:135], v[198:201], v[108:111]
	v_mfma_f32_16x16x32_bf16 v[104:107], v[162:165], v[198:201], v[104:107]
	v_mfma_f32_16x16x32_bf16 v[92:95], v[132:135], v[218:221], v[92:95]
	v_mfma_f32_16x16x32_bf16 v[88:91], v[162:165], v[218:221], v[88:91]
	v_mfma_f32_16x16x32_bf16 v[76:79], v[132:135], v[226:229], v[76:79]
	v_mfma_f32_16x16x32_bf16 v[72:75], v[162:165], v[226:229], v[72:75]
	v_mfma_f32_16x16x32_bf16 v[116:119], v[170:173], v[186:189], v[116:119]
	v_mfma_f32_16x16x32_bf16 v[112:115], v[178:181], v[186:189], v[112:115]
	v_mfma_f32_16x16x32_bf16 v[100:103], v[170:173], v[194:197], v[100:103]
	v_mfma_f32_16x16x32_bf16 v[96:99], v[178:181], v[194:197], v[96:99]
	v_mfma_f32_16x16x32_bf16 v[84:87], v[170:173], v[202:205], v[84:87]
	v_mfma_f32_16x16x32_bf16 v[80:83], v[178:181], v[202:205], v[80:83]
	v_mfma_f32_16x16x32_bf16 v[68:71], v[170:173], v[222:225], v[68:71]
	v_mfma_f32_16x16x32_bf16 v[64:67], v[178:181], v[222:225], v[64:67]
	v_mfma_f32_16x16x32_bf16 v[116:119], v[174:177], v[190:193], v[116:119]
	v_mfma_f32_16x16x32_bf16 v[112:115], v[182:185], v[190:193], v[112:115]
	v_mfma_f32_16x16x32_bf16 v[100:103], v[174:177], v[198:201], v[100:103]
	v_mfma_f32_16x16x32_bf16 v[96:99], v[182:185], v[198:201], v[96:99]
	v_mfma_f32_16x16x32_bf16 v[84:87], v[174:177], v[218:221], v[84:87]
	v_mfma_f32_16x16x32_bf16 v[80:83], v[182:185], v[218:221], v[80:83]
	v_mfma_f32_16x16x32_bf16 v[68:71], v[174:177], v[226:229], v[68:71]
	v_mfma_f32_16x16x32_bf16 v[64:67], v[182:185], v[226:229], v[64:67]
	s_barrier
	s_add_i32 s4, s45, s49
	v_lshl_add_u64 v[146:147], v[146:147], 0, s[28:29]
	s_mov_b32 m0, s4
	ds_read_b128 v[186:189], v169 offset:49152
	ds_read_b128 v[190:193], v169 offset:50176
	ds_read_b128 v[194:197], v169 offset:51200
	ds_read_b128 v[198:201], v169 offset:52224
	ds_read_b128 v[202:205], v169 offset:53248
	ds_read_b128 v[218:221], v169 offset:54272
	ds_read_b128 v[222:225], v169 offset:55296
	ds_read_b128 v[226:229], v169 offset:56320
	global_load_lds_dwordx4 v[146:147], off
	s_add_i32 m0, s4, 0x2000
	s_add_u32 s2, s2, 0xb0080
	v_lshl_add_u64 v[146:147], v[154:155], 0, s[28:29]
	s_addc_u32 s3, s3, 0
	s_add_i32 s4, s62, s49
	global_load_lds_dwordx4 v[146:147], off
	v_lshl_add_u64 v[146:147], s[2:3], 0, v[148:149]
	s_mov_b32 m0, s4
	s_nop 0
	global_load_lds_dwordx4 v[146:147], off
	v_lshl_add_u64 v[146:147], s[2:3], 0, v[136:137]
	s_add_i32 m0, s4, 0x2000
	s_nop 0
	global_load_lds_dwordx4 v[146:147], off
	v_lshl_add_u64 v[146:147], v[156:157], 0, s[28:29]
	s_mov_b32 m0, s57
	s_nop 0
	global_load_lds_dwordx4 v[146:147], off
	v_lshl_add_u64 v[146:147], v[166:167], 0, s[28:29]
	s_mov_b32 m0, s58
	s_nop 0
	global_load_lds_dwordx4 v[146:147], off
	s_waitcnt vmcnt(8)
	s_waitcnt lgkmcnt(0)
	s_barrier
	s_waitcnt lgkmcnt(0)
	v_mfma_f32_16x16x32_bf16 v[60:63], v[128:131], v[186:189], v[60:63]
	v_mfma_f32_16x16x32_bf16 v[56:59], v[158:161], v[186:189], v[56:59]
	v_mfma_f32_16x16x32_bf16 v[44:47], v[128:131], v[194:197], v[44:47]
	v_mfma_f32_16x16x32_bf16 v[40:43], v[158:161], v[194:197], v[40:43]
	v_mfma_f32_16x16x32_bf16 v[28:31], v[128:131], v[202:205], v[28:31]
	v_mfma_f32_16x16x32_bf16 v[24:27], v[158:161], v[202:205], v[24:27]
	v_mfma_f32_16x16x32_bf16 v[12:15], v[128:131], v[222:225], v[12:15]
	v_mfma_f32_16x16x32_bf16 v[8:11], v[158:161], v[222:225], v[8:11]
	v_mfma_f32_16x16x32_bf16 v[60:63], v[132:135], v[190:193], v[60:63]
	v_mfma_f32_16x16x32_bf16 v[56:59], v[162:165], v[190:193], v[56:59]
	v_mfma_f32_16x16x32_bf16 v[44:47], v[132:135], v[198:201], v[44:47]
	v_mfma_f32_16x16x32_bf16 v[40:43], v[162:165], v[198:201], v[40:43]
	v_mfma_f32_16x16x32_bf16 v[28:31], v[132:135], v[218:221], v[28:31]
	v_mfma_f32_16x16x32_bf16 v[24:27], v[162:165], v[218:221], v[24:27]
	v_mfma_f32_16x16x32_bf16 v[12:15], v[132:135], v[226:229], v[12:15]
	v_mfma_f32_16x16x32_bf16 v[8:11], v[162:165], v[226:229], v[8:11]
	v_mfma_f32_16x16x32_bf16 v[52:55], v[170:173], v[186:189], v[52:55]
	v_mfma_f32_16x16x32_bf16 v[48:51], v[178:181], v[186:189], v[48:51]
	v_mfma_f32_16x16x32_bf16 v[36:39], v[170:173], v[194:197], v[36:39]
	v_mfma_f32_16x16x32_bf16 v[32:35], v[178:181], v[194:197], v[32:35]
	v_mfma_f32_16x16x32_bf16 v[20:23], v[170:173], v[202:205], v[20:23]
	v_mfma_f32_16x16x32_bf16 v[16:19], v[178:181], v[202:205], v[16:19]
	v_mfma_f32_16x16x32_bf16 v[4:7], v[170:173], v[222:225], v[4:7]
	v_mfma_f32_16x16x32_bf16 v[0:3], v[178:181], v[222:225], v[0:3]
	v_mfma_f32_16x16x32_bf16 v[52:55], v[174:177], v[190:193], v[52:55]
	v_mfma_f32_16x16x32_bf16 v[48:51], v[182:185], v[190:193], v[48:51]
	v_mfma_f32_16x16x32_bf16 v[36:39], v[174:177], v[198:201], v[36:39]
	v_mfma_f32_16x16x32_bf16 v[32:35], v[182:185], v[198:201], v[32:35]
	v_mfma_f32_16x16x32_bf16 v[20:23], v[174:177], v[218:221], v[20:23]
	v_mfma_f32_16x16x32_bf16 v[16:19], v[182:185], v[218:221], v[16:19]
	v_mfma_f32_16x16x32_bf16 v[4:7], v[174:177], v[226:229], v[4:7]
	v_mfma_f32_16x16x32_bf16 v[0:3], v[182:185], v[226:229], v[0:3]
	s_barrier
	s_add_i32 s44, s44, 2
	s_add_u32 s42, s42, 0x100
	s_addc_u32 s43, s43, 0
	s_cmp_gt_u32 s44, 41
	s_mov_b64 s[4:5], s[0:1]
	s_cbranch_scc0 .LBB0_360
	s_setprio 0
	s_and_b64 vcc, exec, s[30:31]
	s_cbranch_vccz .LBB0_363
	s_barrier

.LBB0_587:
	s_ashr_i32 s37, s36, 31
	s_lshl_b64 s[14:15], s[36:37], 19
	s_add_u32 s38, s90, s14
	s_addc_u32 s39, s91, s15
	s_and_b64 s[14:15], s[6:7], exec
	s_cselect_b32 s9, s39, s11
	s_cselect_b32 s16, s38, s10
	s_ashr_i32 s35, s34, 31
	s_lshl_b64 s[14:15], s[34:35], 19
	s_add_u32 s40, s0, s14
	s_addc_u32 s41, s1, s15
	s_and_b64 s[14:15], s[6:7], exec
	s_cselect_b32 s17, s41, s13
	s_cselect_b32 s35, s40, s12
	s_add_u32 s10, s10, 0x40080
	s_addc_u32 s11, s11, 0
	s_add_u32 s37, s12, 0x100
	v_mov_b32_e32 v0, 0
	s_addc_u32 s42, s13, 0
	s_mov_b32 s43, -2
	v_mov_b32_e32 v1, v0
	v_mov_b32_e32 v2, v0
	s_waitcnt lgkmcnt(0)
	v_mov_b32_e32 v3, v0
	v_mov_b32_e32 v4, v0
	v_mov_b32_e32 v5, v0
	v_mov_b32_e32 v6, v0
	v_mov_b32_e32 v7, v0
	v_mov_b32_e32 v16, v0
	v_mov_b32_e32 v17, v0
	v_mov_b32_e32 v18, v0
	v_mov_b32_e32 v19, v0
	v_mov_b32_e32 v20, v0
	v_mov_b32_e32 v21, v0
	v_mov_b32_e32 v22, v0
	v_mov_b32_e32 v23, v0
	v_mov_b32_e32 v32, v0
	v_mov_b32_e32 v33, v0
	v_mov_b32_e32 v34, v0
	v_mov_b32_e32 v35, v0
	v_mov_b32_e32 v36, v0
	v_mov_b32_e32 v37, v0
	v_mov_b32_e32 v38, v0
	v_mov_b32_e32 v39, v0
	v_mov_b32_e32 v48, v0
	v_mov_b32_e32 v49, v0
	v_mov_b32_e32 v50, v0
	v_mov_b32_e32 v51, v0
	v_mov_b32_e32 v52, v0
	v_mov_b32_e32 v53, v0
	v_mov_b32_e32 v54, v0
	v_mov_b32_e32 v55, v0
	v_mov_b32_e32 v8, v0
	v_mov_b32_e32 v9, v0
	v_mov_b32_e32 v10, v0
	v_mov_b32_e32 v11, v0
	v_mov_b32_e32 v12, v0
	v_mov_b32_e32 v13, v0
	v_mov_b32_e32 v14, v0
	v_mov_b32_e32 v15, v0
	v_mov_b32_e32 v24, v0
	v_mov_b32_e32 v25, v0
	v_mov_b32_e32 v26, v0
	v_mov_b32_e32 v27, v0
	v_mov_b32_e32 v28, v0
	v_mov_b32_e32 v29, v0
	v_mov_b32_e32 v30, v0
	v_mov_b32_e32 v31, v0
	v_mov_b32_e32 v40, v0
	v_mov_b32_e32 v41, v0
	v_mov_b32_e32 v42, v0
	v_mov_b32_e32 v43, v0
	v_mov_b32_e32 v44, v0
	v_mov_b32_e32 v45, v0
	v_mov_b32_e32 v46, v0
	v_mov_b32_e32 v47, v0
	v_mov_b32_e32 v56, v0
	v_mov_b32_e32 v57, v0
	v_mov_b32_e32 v58, v0
	v_mov_b32_e32 v59, v0
	v_mov_b32_e32 v60, v0
	v_mov_b32_e32 v61, v0
	v_mov_b32_e32 v62, v0
	v_mov_b32_e32 v63, v0
	v_mov_b32_e32 v64, v0
	v_mov_b32_e32 v65, v0
	v_mov_b32_e32 v66, v0
	v_mov_b32_e32 v67, v0
	v_mov_b32_e32 v68, v0
	v_mov_b32_e32 v69, v0
	v_mov_b32_e32 v70, v0
	v_mov_b32_e32 v71, v0
	v_mov_b32_e32 v80, v0
	v_mov_b32_e32 v81, v0
	v_mov_b32_e32 v82, v0
	v_mov_b32_e32 v83, v0
	v_mov_b32_e32 v84, v0
	v_mov_b32_e32 v85, v0
	v_mov_b32_e32 v86, v0
	v_mov_b32_e32 v87, v0
	v_mov_b32_e32 v96, v0
	v_mov_b32_e32 v97, v0
	v_mov_b32_e32 v98, v0
	v_mov_b32_e32 v99, v0
	v_mov_b32_e32 v100, v0
	v_mov_b32_e32 v101, v0
	v_mov_b32_e32 v102, v0
	v_mov_b32_e32 v103, v0
	v_mov_b32_e32 v112, v0
	v_mov_b32_e32 v113, v0
	v_mov_b32_e32 v114, v0
	v_mov_b32_e32 v115, v0
	v_mov_b32_e32 v116, v0
	v_mov_b32_e32 v117, v0
	v_mov_b32_e32 v118, v0
	v_mov_b32_e32 v119, v0
	v_mov_b32_e32 v72, v0
	v_mov_b32_e32 v73, v0
	v_mov_b32_e32 v74, v0
	v_mov_b32_e32 v75, v0
	v_mov_b32_e32 v76, v0
	v_mov_b32_e32 v77, v0
	v_mov_b32_e32 v78, v0
	v_mov_b32_e32 v79, v0
	v_mov_b32_e32 v88, v0
	v_mov_b32_e32 v89, v0
	v_mov_b32_e32 v90, v0
	v_mov_b32_e32 v91, v0
	v_mov_b32_e32 v92, v0
	v_mov_b32_e32 v93, v0
	v_mov_b32_e32 v94, v0
	v_mov_b32_e32 v95, v0
	v_mov_b32_e32 v104, v0
	v_mov_b32_e32 v105, v0
	v_mov_b32_e32 v106, v0
	v_mov_b32_e32 v107, v0
	v_mov_b32_e32 v108, v0
	v_mov_b32_e32 v109, v0
	v_mov_b32_e32 v110, v0
	v_mov_b32_e32 v111, v0
	v_mov_b32_e32 v120, v0
	v_mov_b32_e32 v121, v0
	v_mov_b32_e32 v122, v0
	v_mov_b32_e32 v123, v0
	v_mov_b32_e32 v124, v0
	v_mov_b32_e32 v125, v0
	v_mov_b32_e32 v126, v0
	v_mov_b32_e32 v127, v0
	v_readfirstlane_b32 s100, v206
	s_nop 0
	s_cmp_lt_u32 s100, 0x100
	s_cbranch_scc1 .Lprio_skip_2
	s_setprio 1

.LBB0_588:
	s_add_u32 s12, s10, 0xfffc0080
	s_addc_u32 s13, s11, -1
	s_add_i32 s44, 0, 0x10000
	s_cmp_eq_u32 s43, 12
	s_cselect_b32 s15, s9, s13
	s_cselect_b32 s14, s16, s12
	v_add_u32_e32 v146, s44, v144
	s_cselect_b32 s13, s17, s42
	s_cselect_b32 s12, s35, s37
	s_add_i32 s46, 0, 0x14000
	ds_read_b128 v[140:143], v146
	ds_read_b128 v[158:161], v146 offset:1024
	ds_read_b128 v[162:165], v146 offset:2048
	ds_read_b128 v[166:169], v146 offset:3072
	v_add_u32_e32 v146, s46, v144
	ds_read_b128 v[174:177], v146
	ds_read_b128 v[178:181], v146 offset:1024
	ds_read_b128 v[182:185], v146 offset:2048
	ds_read_b128 v[186:189], v146 offset:3072
	v_lshl_add_u64 v[146:147], s[10:11], 0, v[136:137]
	s_add_i32 m0, s57, 0xc000
	ds_read_b128 v[190:193], v145
	ds_read_b128 v[194:197], v145 offset:1024
	ds_read_b128 v[198:201], v145 offset:2048
	ds_read_b128 v[202:205], v145 offset:3072
	ds_read_b128 v[218:221], v145 offset:4096
	ds_read_b128 v[222:225], v145 offset:5120
	ds_read_b128 v[226:229], v145 offset:6144
	ds_read_b128 v[230:233], v145 offset:7168
	global_load_lds_dwordx4 v[146:147], off
	v_lshl_add_u64 v[146:147], s[10:11], 0, v[138:139]
	s_add_i32 m0, s57, 0xe000
	s_nop 0
	global_load_lds_dwordx4 v[146:147], off
	s_waitcnt vmcnt(8)
	s_waitcnt lgkmcnt(0)
	s_barrier
	s_waitcnt lgkmcnt(0)
	v_mfma_f32_16x16x32_bf16 v[124:127], v[140:143], v[190:193], v[124:127]
	v_mfma_f32_16x16x32_bf16 v[120:123], v[162:165], v[190:193], v[120:123]
	v_mfma_f32_16x16x32_bf16 v[108:111], v[140:143], v[198:201], v[108:111]
	v_mfma_f32_16x16x32_bf16 v[104:107], v[162:165], v[198:201], v[104:107]
	v_mfma_f32_16x16x32_bf16 v[92:95], v[140:143], v[218:221], v[92:95]
	v_mfma_f32_16x16x32_bf16 v[88:91], v[162:165], v[218:221], v[88:91]
	v_mfma_f32_16x16x32_bf16 v[76:79], v[140:143], v[226:229], v[76:79]
	v_mfma_f32_16x16x32_bf16 v[72:75], v[162:165], v[226:229], v[72:75]
	v_mfma_f32_16x16x32_bf16 v[124:127], v[158:161], v[194:197], v[124:127]
	v_mfma_f32_16x16x32_bf16 v[120:123], v[166:169], v[194:197], v[120:123]
	v_mfma_f32_16x16x32_bf16 v[108:111], v[158:161], v[202:205], v[108:111]
	v_mfma_f32_16x16x32_bf16 v[104:107], v[166:169], v[202:205], v[104:107]
	v_mfma_f32_16x16x32_bf16 v[92:95], v[158:161], v[222:225], v[92:95]
	v_mfma_f32_16x16x32_bf16 v[88:91], v[166:169], v[222:225], v[88:91]
	v_mfma_f32_16x16x32_bf16 v[76:79], v[158:161], v[230:233], v[76:79]
	v_mfma_f32_16x16x32_bf16 v[72:75], v[166:169], v[230:233], v[72:75]
	v_mfma_f32_16x16x32_bf16 v[116:119], v[174:177], v[190:193], v[116:119]
	v_mfma_f32_16x16x32_bf16 v[112:115], v[182:185], v[190:193], v[112:115]
	v_mfma_f32_16x16x32_bf16 v[100:103], v[174:177], v[198:201], v[100:103]
	v_mfma_f32_16x16x32_bf16 v[96:99], v[182:185], v[198:201], v[96:99]
	v_mfma_f32_16x16x32_bf16 v[84:87], v[174:177], v[218:221], v[84:87]
	v_mfma_f32_16x16x32_bf16 v[80:83], v[182:185], v[218:221], v[80:83]
	v_mfma_f32_16x16x32_bf16 v[68:71], v[174:177], v[226:229], v[68:71]
	v_mfma_f32_16x16x32_bf16 v[64:67], v[182:185], v[226:229], v[64:67]
	v_mfma_f32_16x16x32_bf16 v[116:119], v[178:181], v[194:197], v[116:119]
	v_mfma_f32_16x16x32_bf16 v[112:115], v[186:189], v[194:197], v[112:115]
	v_mfma_f32_16x16x32_bf16 v[100:103], v[178:181], v[202:205], v[100:103]
	v_mfma_f32_16x16x32_bf16 v[96:99], v[186:189], v[202:205], v[96:99]
	v_mfma_f32_16x16x32_bf16 v[84:87], v[178:181], v[222:225], v[84:87]
	v_mfma_f32_16x16x32_bf16 v[80:83], v[186:189], v[222:225], v[80:83]
	v_mfma_f32_16x16x32_bf16 v[68:71], v[178:181], v[230:233], v[68:71]
	v_mfma_f32_16x16x32_bf16 v[64:67], v[186:189], v[230:233], v[64:67]
	s_barrier
	s_add_i32 s44, s44, s56
	v_lshl_add_u64 v[146:147], s[12:13], 0, v[132:133]
	s_mov_b32 m0, s44
	ds_read_b128 v[190:193], v145 offset:16384
	ds_read_b128 v[194:197], v145 offset:17408
	ds_read_b128 v[198:201], v145 offset:18432
	ds_read_b128 v[202:205], v145 offset:19456
	ds_read_b128 v[218:221], v145 offset:20480
	ds_read_b128 v[222:225], v145 offset:21504
	ds_read_b128 v[226:229], v145 offset:22528
	ds_read_b128 v[230:233], v145 offset:23552
	global_load_lds_dwordx4 v[146:147], off
	s_add_i32 m0, s44, 0x2000
	s_add_u32 s44, s12, 0x40000
	v_lshl_add_u64 v[154:155], s[12:13], 0, v[128:129]
	s_addc_u32 s45, s13, 0
	s_add_i32 s46, s46, s56
	global_load_lds_dwordx4 v[154:155], off
	v_lshl_add_u64 v[156:157], s[44:45], 0, v[132:133]
	s_mov_b32 m0, s46
	v_lshl_add_u64 v[170:171], s[14:15], 0, v[130:131]
	global_load_lds_dwordx4 v[156:157], off
	v_lshl_add_u64 v[156:157], s[44:45], 0, v[128:129]
	s_add_i32 m0, s46, 0x2000
	s_nop 0
	global_load_lds_dwordx4 v[156:157], off
	v_lshl_add_u64 v[156:157], s[14:15], 0, v[134:135]
	s_mov_b32 m0, s57
	s_nop 0
	global_load_lds_dwordx4 v[156:157], off
	s_mov_b32 m0, s58
	s_nop 0
	global_load_lds_dwordx4 v[170:171], off
	s_waitcnt vmcnt(8)
	s_waitcnt lgkmcnt(0)
	s_barrier
	s_waitcnt lgkmcnt(0)
	v_mfma_f32_16x16x32_bf16 v[60:63], v[140:143], v[190:193], v[60:63]
	v_mfma_f32_16x16x32_bf16 v[56:59], v[162:165], v[190:193], v[56:59]
	v_mfma_f32_16x16x32_bf16 v[44:47], v[140:143], v[198:201], v[44:47]
	v_mfma_f32_16x16x32_bf16 v[40:43], v[162:165], v[198:201], v[40:43]
	v_mfma_f32_16x16x32_bf16 v[28:31], v[140:143], v[218:221], v[28:31]
	v_mfma_f32_16x16x32_bf16 v[24:27], v[162:165], v[218:221], v[24:27]
	v_mfma_f32_16x16x32_bf16 v[12:15], v[140:143], v[226:229], v[12:15]
	v_mfma_f32_16x16x32_bf16 v[8:11], v[162:165], v[226:229], v[8:11]
	v_mfma_f32_16x16x32_bf16 v[60:63], v[158:161], v[194:197], v[60:63]
	v_mfma_f32_16x16x32_bf16 v[56:59], v[166:169], v[194:197], v[56:59]
	v_mfma_f32_16x16x32_bf16 v[44:47], v[158:161], v[202:205], v[44:47]
	v_mfma_f32_16x16x32_bf16 v[40:43], v[166:169], v[202:205], v[40:43]
	v_mfma_f32_16x16x32_bf16 v[28:31], v[158:161], v[222:225], v[28:31]
	v_mfma_f32_16x16x32_bf16 v[24:27], v[166:169], v[222:225], v[24:27]
	v_mfma_f32_16x16x32_bf16 v[12:15], v[158:161], v[230:233], v[12:15]
	v_mfma_f32_16x16x32_bf16 v[8:11], v[166:169], v[230:233], v[8:11]
	v_mfma_f32_16x16x32_bf16 v[52:55], v[174:177], v[190:193], v[52:55]
	v_mfma_f32_16x16x32_bf16 v[48:51], v[182:185], v[190:193], v[48:51]
	v_mfma_f32_16x16x32_bf16 v[36:39], v[174:177], v[198:201], v[36:39]
	v_mfma_f32_16x16x32_bf16 v[32:35], v[182:185], v[198:201], v[32:35]
	v_mfma_f32_16x16x32_bf16 v[20:23], v[174:177], v[218:221], v[20:23]
	v_mfma_f32_16x16x32_bf16 v[16:19], v[182:185], v[218:221], v[16:19]
	v_mfma_f32_16x16x32_bf16 v[4:7], v[174:177], v[226:229], v[4:7]
	v_mfma_f32_16x16x32_bf16 v[0:3], v[182:185], v[226:229], v[0:3]
	v_mfma_f32_16x16x32_bf16 v[52:55], v[178:181], v[194:197], v[52:55]
	v_mfma_f32_16x16x32_bf16 v[48:51], v[186:189], v[194:197], v[48:51]
	v_mfma_f32_16x16x32_bf16 v[36:39], v[178:181], v[202:205], v[36:39]
	v_mfma_f32_16x16x32_bf16 v[32:35], v[186:189], v[202:205], v[32:35]
	v_mfma_f32_16x16x32_bf16 v[20:23], v[178:181], v[222:225], v[20:23]
	v_mfma_f32_16x16x32_bf16 v[16:19], v[186:189], v[222:225], v[16:19]
	v_mfma_f32_16x16x32_bf16 v[4:7], v[178:181], v[230:233], v[4:7]
	v_mfma_f32_16x16x32_bf16 v[0:3], v[186:189], v[230:233], v[0:3]
	s_barrier
	s_add_i32 s44, 0, 0x18000
	v_add_u32_e32 v148, s44, v144
	s_add_i32 s45, 0, 0x1c000
	ds_read_b128 v[140:143], v148
	ds_read_b128 v[158:161], v148 offset:1024
	ds_read_b128 v[162:165], v148 offset:2048
	ds_read_b128 v[166:169], v148 offset:3072
	v_add_u32_e32 v148, s45, v144
	ds_read_b128 v[174:177], v148
	ds_read_b128 v[178:181], v148 offset:1024
	ds_read_b128 v[182:185], v148 offset:2048
	ds_read_b128 v[186:189], v148 offset:3072
	s_add_u32 s14, s14, 0x40000
	s_addc_u32 s15, s15, 0
	s_mov_b32 m0, s59
	v_lshl_add_u64 v[212:213], s[14:15], 0, v[134:135]
	ds_read_b128 v[190:193], v145 offset:32768
	ds_read_b128 v[194:197], v145 offset:33792
	ds_read_b128 v[198:201], v145 offset:34816
	ds_read_b128 v[202:205], v145 offset:35840
	ds_read_b128 v[218:221], v145 offset:36864
	ds_read_b128 v[222:225], v145 offset:37888
	ds_read_b128 v[226:229], v145 offset:38912
	ds_read_b128 v[230:233], v145 offset:39936
	global_load_lds_dwordx4 v[212:213], off
	v_lshl_add_u64 v[212:213], s[14:15], 0, v[130:131]
	s_mov_b32 m0, s60
	s_nop 0
	global_load_lds_dwordx4 v[212:213], off
	s_waitcnt vmcnt(8)
	s_waitcnt lgkmcnt(0)
	s_barrier
	s_waitcnt lgkmcnt(0)
	v_mfma_f32_16x16x32_bf16 v[124:127], v[140:143], v[190:193], v[124:127]
	v_mfma_f32_16x16x32_bf16 v[120:123], v[162:165], v[190:193], v[120:123]
	v_mfma_f32_16x16x32_bf16 v[108:111], v[140:143], v[198:201], v[108:111]
	v_mfma_f32_16x16x32_bf16 v[104:107], v[162:165], v[198:201], v[104:107]
	v_mfma_f32_16x16x32_bf16 v[92:95], v[140:143], v[218:221], v[92:95]
	v_mfma_f32_16x16x32_bf16 v[88:91], v[162:165], v[218:221], v[88:91]
	v_mfma_f32_16x16x32_bf16 v[76:79], v[140:143], v[226:229], v[76:79]
	v_mfma_f32_16x16x32_bf16 v[72:75], v[162:165], v[226:229], v[72:75]
	v_mfma_f32_16x16x32_bf16 v[124:127], v[158:161], v[194:197], v[124:127]
	v_mfma_f32_16x16x32_bf16 v[120:123], v[166:169], v[194:197], v[120:123]
	v_mfma_f32_16x16x32_bf16 v[108:111], v[158:161], v[202:205], v[108:111]
	v_mfma_f32_16x16x32_bf16 v[104:107], v[166:169], v[202:205], v[104:107]
	v_mfma_f32_16x16x32_bf16 v[92:95], v[158:161], v[222:225], v[92:95]
	v_mfma_f32_16x16x32_bf16 v[88:91], v[166:169], v[222:225], v[88:91]
	v_mfma_f32_16x16x32_bf16 v[76:79], v[158:161], v[230:233], v[76:79]
	v_mfma_f32_16x16x32_bf16 v[72:75], v[166:169], v[230:233], v[72:75]
	v_mfma_f32_16x16x32_bf16 v[116:119], v[174:177], v[190:193], v[116:119]
	v_mfma_f32_16x16x32_bf16 v[112:115], v[182:185], v[190:193], v[112:115]
	v_mfma_f32_16x16x32_bf16 v[100:103], v[174:177], v[198:201], v[100:103]
	v_mfma_f32_16x16x32_bf16 v[96:99], v[182:185], v[198:201], v[96:99]
	v_mfma_f32_16x16x32_bf16 v[84:87], v[174:177], v[218:221], v[84:87]
	v_mfma_f32_16x16x32_bf16 v[80:83], v[182:185], v[218:221], v[80:83]
	v_mfma_f32_16x16x32_bf16 v[68:71], v[174:177], v[226:229], v[68:71]
	v_mfma_f32_16x16x32_bf16 v[64:67], v[182:185], v[226:229], v[64:67]
	v_mfma_f32_16x16x32_bf16 v[116:119], v[178:181], v[194:197], v[116:119]
	v_mfma_f32_16x16x32_bf16 v[112:115], v[186:189], v[194:197], v[112:115]
	v_mfma_f32_16x16x32_bf16 v[100:103], v[178:181], v[202:205], v[100:103]
	v_mfma_f32_16x16x32_bf16 v[96:99], v[186:189], v[202:205], v[96:99]
	v_mfma_f32_16x16x32_bf16 v[84:87], v[178:181], v[222:225], v[84:87]
	v_mfma_f32_16x16x32_bf16 v[80:83], v[186:189], v[222:225], v[80:83]
	v_mfma_f32_16x16x32_bf16 v[68:71], v[178:181], v[230:233], v[68:71]
	v_mfma_f32_16x16x32_bf16 v[64:67], v[186:189], v[230:233], v[64:67]
	s_barrier
	s_add_i32 s14, s44, s56
	v_lshl_add_u64 v[146:147], v[146:147], 0, s[28:29]
	s_mov_b32 m0, s14
	ds_read_b128 v[190:193], v145 offset:49152
	ds_read_b128 v[194:197], v145 offset:50176
	ds_read_b128 v[198:201], v145 offset:51200
	ds_read_b128 v[202:205], v145 offset:52224
	ds_read_b128 v[218:221], v145 offset:53248
	ds_read_b128 v[222:225], v145 offset:54272
	ds_read_b128 v[226:229], v145 offset:55296
	ds_read_b128 v[230:233], v145 offset:56320
	global_load_lds_dwordx4 v[146:147], off
	s_add_i32 m0, s14, 0x2000
	s_add_u32 s12, s12, 0x40080
	v_lshl_add_u64 v[146:147], v[154:155], 0, s[28:29]
	s_addc_u32 s13, s13, 0
	s_add_i32 s14, s45, s56
	global_load_lds_dwordx4 v[146:147], off
	v_lshl_add_u64 v[146:147], s[12:13], 0, v[132:133]
	s_mov_b32 m0, s14
	s_nop 0
	global_load_lds_dwordx4 v[146:147], off
	v_lshl_add_u64 v[146:147], s[12:13], 0, v[128:129]
	s_add_i32 m0, s14, 0x2000
	s_nop 0
	global_load_lds_dwordx4 v[146:147], off
	v_lshl_add_u64 v[146:147], v[156:157], 0, s[28:29]
	s_mov_b32 m0, s72
	s_nop 0
	global_load_lds_dwordx4 v[146:147], off
	v_lshl_add_u64 v[146:147], v[170:171], 0, s[28:29]
	s_mov_b32 m0, s73
	s_nop 0
	global_load_lds_dwordx4 v[146:147], off
	s_waitcnt vmcnt(8)
	s_waitcnt lgkmcnt(0)
	s_barrier
	s_waitcnt lgkmcnt(0)
	v_mfma_f32_16x16x32_bf16 v[60:63], v[140:143], v[190:193], v[60:63]
	v_mfma_f32_16x16x32_bf16 v[56:59], v[162:165], v[190:193], v[56:59]
	v_mfma_f32_16x16x32_bf16 v[44:47], v[140:143], v[198:201], v[44:47]
	v_mfma_f32_16x16x32_bf16 v[40:43], v[162:165], v[198:201], v[40:43]
	v_mfma_f32_16x16x32_bf16 v[28:31], v[140:143], v[218:221], v[28:31]
	v_mfma_f32_16x16x32_bf16 v[24:27], v[162:165], v[218:221], v[24:27]
	v_mfma_f32_16x16x32_bf16 v[12:15], v[140:143], v[226:229], v[12:15]
	v_mfma_f32_16x16x32_bf16 v[8:11], v[162:165], v[226:229], v[8:11]
	v_mfma_f32_16x16x32_bf16 v[60:63], v[158:161], v[194:197], v[60:63]
	v_mfma_f32_16x16x32_bf16 v[56:59], v[166:169], v[194:197], v[56:59]
	v_mfma_f32_16x16x32_bf16 v[44:47], v[158:161], v[202:205], v[44:47]
	v_mfma_f32_16x16x32_bf16 v[40:43], v[166:169], v[202:205], v[40:43]
	v_mfma_f32_16x16x32_bf16 v[28:31], v[158:161], v[222:225], v[28:31]
	v_mfma_f32_16x16x32_bf16 v[24:27], v[166:169], v[222:225], v[24:27]
	v_mfma_f32_16x16x32_bf16 v[12:15], v[158:161], v[230:233], v[12:15]
	v_mfma_f32_16x16x32_bf16 v[8:11], v[166:169], v[230:233], v[8:11]
	v_mfma_f32_16x16x32_bf16 v[52:55], v[174:177], v[190:193], v[52:55]
	v_mfma_f32_16x16x32_bf16 v[48:51], v[182:185], v[190:193], v[48:51]
	v_mfma_f32_16x16x32_bf16 v[36:39], v[174:177], v[198:201], v[36:39]
	v_mfma_f32_16x16x32_bf16 v[32:35], v[182:185], v[198:201], v[32:35]
	v_mfma_f32_16x16x32_bf16 v[20:23], v[174:177], v[218:221], v[20:23]
	v_mfma_f32_16x16x32_bf16 v[16:19], v[182:185], v[218:221], v[16:19]
	v_mfma_f32_16x16x32_bf16 v[4:7], v[174:177], v[226:229], v[4:7]
	v_mfma_f32_16x16x32_bf16 v[0:3], v[182:185], v[226:229], v[0:3]
	v_mfma_f32_16x16x32_bf16 v[52:55], v[178:181], v[194:197], v[52:55]
	v_mfma_f32_16x16x32_bf16 v[48:51], v[186:189], v[194:197], v[48:51]
	v_mfma_f32_16x16x32_bf16 v[36:39], v[178:181], v[202:205], v[36:39]
	v_mfma_f32_16x16x32_bf16 v[32:35], v[186:189], v[202:205], v[32:35]
	v_mfma_f32_16x16x32_bf16 v[20:23], v[178:181], v[222:225], v[20:23]
	v_mfma_f32_16x16x32_bf16 v[16:19], v[186:189], v[222:225], v[16:19]
	v_mfma_f32_16x16x32_bf16 v[4:7], v[178:181], v[230:233], v[4:7]
	v_mfma_f32_16x16x32_bf16 v[0:3], v[186:189], v[230:233], v[0:3]
	s_barrier
	s_add_i32 s43, s43, 2
	s_add_u32 s10, s10, 0x100
	s_addc_u32 s11, s11, 0
	s_add_u32 s37, s37, 0x100
	s_addc_u32 s42, s42, 0
	s_cmp_gt_u32 s43, 13
	s_cbranch_scc0 .LBB0_588
	s_setprio 0
	s_and_b64 vcc, exec, s[26:27]
	s_cbranch_vccz .LBB0_591
	s_barrier

.LBB0_763:
	s_ashr_i32 s21, s20, 31
	s_lshl_b64 s[22:23], s[20:21], 19
	s_add_u32 s22, s10, s22
	s_addc_u32 s23, s11, s23
	s_and_b64 s[24:25], s[8:9], exec
	s_cselect_b32 s21, s23, s27
	s_cselect_b32 s48, s22, s26
	s_ashr_i32 s19, s18, 31
	s_lshl_b64 s[24:25], s[18:19], 19
	s_add_u32 s24, s90, s24
	s_addc_u32 s25, s91, s25
	s_and_b64 s[34:35], s[8:9], exec
	s_mov_b32 s57, s49
	s_cselect_b32 s19, s25, s31
	s_cselect_b32 s49, s24, s30
	s_add_u32 s26, s26, 0x40080
	s_addc_u32 s27, s27, 0
	s_add_u32 s50, s30, 0x100
	v_mov_b32_e32 v0, 0
	s_addc_u32 s51, s31, 0
	s_mov_b32 s52, -2
	v_mov_b32_e32 v1, v0
	v_mov_b32_e32 v2, v0
	v_mov_b32_e32 v3, v0
	v_mov_b32_e32 v32, v0
	v_mov_b32_e32 v33, v0
	v_mov_b32_e32 v34, v0
	v_mov_b32_e32 v35, v0
	v_mov_b32_e32 v4, v0
	v_mov_b32_e32 v5, v0
	v_mov_b32_e32 v6, v0
	v_mov_b32_e32 v7, v0
	v_mov_b32_e32 v36, v0
	v_mov_b32_e32 v37, v0
	v_mov_b32_e32 v38, v0
	v_mov_b32_e32 v39, v0
	v_mov_b32_e32 v8, v0
	v_mov_b32_e32 v9, v0
	v_mov_b32_e32 v10, v0
	v_mov_b32_e32 v11, v0
	v_mov_b32_e32 v40, v0
	v_mov_b32_e32 v41, v0
	v_mov_b32_e32 v42, v0
	v_mov_b32_e32 v43, v0
	v_mov_b32_e32 v12, v0
	v_mov_b32_e32 v13, v0
	v_mov_b32_e32 v14, v0
	v_mov_b32_e32 v15, v0
	v_mov_b32_e32 v44, v0
	v_mov_b32_e32 v45, v0
	v_mov_b32_e32 v46, v0
	v_mov_b32_e32 v47, v0
	v_mov_b32_e32 v64, v0
	v_mov_b32_e32 v65, v0
	v_mov_b32_e32 v66, v0
	v_mov_b32_e32 v67, v0
	v_mov_b32_e32 v96, v0
	v_mov_b32_e32 v97, v0
	v_mov_b32_e32 v98, v0
	v_mov_b32_e32 v99, v0
	v_mov_b32_e32 v68, v0
	v_mov_b32_e32 v69, v0
	v_mov_b32_e32 v70, v0
	v_mov_b32_e32 v71, v0
	v_mov_b32_e32 v100, v0
	v_mov_b32_e32 v101, v0
	v_mov_b32_e32 v102, v0
	v_mov_b32_e32 v103, v0
	v_mov_b32_e32 v72, v0
	v_mov_b32_e32 v73, v0
	v_mov_b32_e32 v74, v0
	v_mov_b32_e32 v75, v0
	v_mov_b32_e32 v104, v0
	v_mov_b32_e32 v105, v0
	v_mov_b32_e32 v106, v0
	v_mov_b32_e32 v107, v0
	v_mov_b32_e32 v76, v0
	v_mov_b32_e32 v77, v0
	v_mov_b32_e32 v78, v0
	v_mov_b32_e32 v79, v0
	v_mov_b32_e32 v108, v0
	v_mov_b32_e32 v109, v0
	v_mov_b32_e32 v110, v0
	v_mov_b32_e32 v111, v0
	v_mov_b32_e32 v16, v0
	v_mov_b32_e32 v17, v0
	v_mov_b32_e32 v18, v0
	v_mov_b32_e32 v19, v0
	v_mov_b32_e32 v48, v0
	v_mov_b32_e32 v49, v0
	v_mov_b32_e32 v50, v0
	v_mov_b32_e32 v51, v0
	v_mov_b32_e32 v20, v0
	v_mov_b32_e32 v21, v0
	v_mov_b32_e32 v22, v0
	v_mov_b32_e32 v23, v0
	v_mov_b32_e32 v52, v0
	v_mov_b32_e32 v53, v0
	v_mov_b32_e32 v54, v0
	v_mov_b32_e32 v55, v0
	v_mov_b32_e32 v24, v0
	v_mov_b32_e32 v25, v0
	v_mov_b32_e32 v26, v0
	v_mov_b32_e32 v27, v0
	v_mov_b32_e32 v56, v0
	v_mov_b32_e32 v57, v0
	v_mov_b32_e32 v58, v0
	v_mov_b32_e32 v59, v0
	v_mov_b32_e32 v28, v0
	v_mov_b32_e32 v29, v0
	v_mov_b32_e32 v30, v0
	v_mov_b32_e32 v31, v0
	v_mov_b32_e32 v60, v0
	v_mov_b32_e32 v61, v0
	v_mov_b32_e32 v62, v0
	v_mov_b32_e32 v63, v0
	v_mov_b32_e32 v80, v0
	v_mov_b32_e32 v81, v0
	v_mov_b32_e32 v82, v0
	v_mov_b32_e32 v83, v0
	v_mov_b32_e32 v112, v0
	v_mov_b32_e32 v113, v0
	v_mov_b32_e32 v114, v0
	v_mov_b32_e32 v115, v0
	v_mov_b32_e32 v84, v0
	v_mov_b32_e32 v85, v0
	v_mov_b32_e32 v86, v0
	v_mov_b32_e32 v87, v0
	v_mov_b32_e32 v116, v0
	v_mov_b32_e32 v117, v0
	v_mov_b32_e32 v118, v0
	v_mov_b32_e32 v119, v0
	v_mov_b32_e32 v88, v0
	v_mov_b32_e32 v89, v0
	v_mov_b32_e32 v90, v0
	v_mov_b32_e32 v91, v0
	v_mov_b32_e32 v120, v0
	v_mov_b32_e32 v121, v0
	v_mov_b32_e32 v122, v0
	v_mov_b32_e32 v123, v0
	v_mov_b32_e32 v92, v0
	v_mov_b32_e32 v93, v0
	v_mov_b32_e32 v94, v0
	v_mov_b32_e32 v95, v0
	v_mov_b32_e32 v124, v0
	v_mov_b32_e32 v125, v0
	v_mov_b32_e32 v126, v0
	v_mov_b32_e32 v127, v0
	v_readfirstlane_b32 s100, v206
	s_nop 0
	s_cmp_lt_u32 s100, 0x100
	s_cbranch_scc1 .Lprio_skip_3
	s_setprio 1

.LBB0_764:
	s_add_u32 s30, s26, 0xfffc0080
	s_addc_u32 s31, s27, -1
	s_add_i32 s53, 0, 0x10000
	s_cmp_eq_u32 s52, 12
	s_cselect_b32 s35, s21, s31
	s_cselect_b32 s34, s48, s30
	s_cselect_b32 s31, s19, s51
	s_cselect_b32 s30, s49, s50
	s_add_i32 s56, 0, 0x14000
	v_add_u32_e32 v140, s53, v173
	v_add_u32_e32 v150, s56, v173
	ds_read_b128 v[128:131], v140
	ds_read_b128 v[132:135], v140 offset:1024
	ds_read_b128 v[136:139], v140 offset:2048
	ds_read_b128 v[140:143], v140 offset:3072
	ds_read_b128 v[164:167], v150
	ds_read_b128 v[168:171], v150 offset:1024
	ds_read_b128 v[176:179], v150 offset:2048
	ds_read_b128 v[180:183], v150 offset:3072
	v_lshl_add_u64 v[154:155], s[26:27], 0, v[160:161]
	s_add_i32 m0, s37, 0xc000
	ds_read_b128 v[184:187], v174
	ds_read_b128 v[188:191], v174 offset:1024
	ds_read_b128 v[192:195], v174 offset:2048
	ds_read_b128 v[196:199], v174 offset:3072
	ds_read_b128 v[200:203], v174 offset:4096
	ds_read_b128 v[218:221], v174 offset:5120
	ds_read_b128 v[222:225], v174 offset:6144
	ds_read_b128 v[226:229], v174 offset:7168
	global_load_lds_dwordx4 v[154:155], off
	v_lshl_add_u64 v[154:155], s[26:27], 0, v[162:163]
	s_add_i32 m0, s37, 0xe000
	s_nop 0
	global_load_lds_dwordx4 v[154:155], off
	s_waitcnt vmcnt(8)
	s_waitcnt lgkmcnt(0)
	s_barrier
	s_waitcnt lgkmcnt(0)
	v_mfma_f32_16x16x32_bf16 v[124:127], v[128:131], v[184:187], v[124:127]
	v_mfma_f32_16x16x32_bf16 v[92:95], v[136:139], v[184:187], v[92:95]
	v_mfma_f32_16x16x32_bf16 v[120:123], v[128:131], v[192:195], v[120:123]
	v_mfma_f32_16x16x32_bf16 v[88:91], v[136:139], v[192:195], v[88:91]
	v_mfma_f32_16x16x32_bf16 v[116:119], v[128:131], v[200:203], v[116:119]
	v_mfma_f32_16x16x32_bf16 v[84:87], v[136:139], v[200:203], v[84:87]
	v_mfma_f32_16x16x32_bf16 v[112:115], v[128:131], v[222:225], v[112:115]
	v_mfma_f32_16x16x32_bf16 v[80:83], v[136:139], v[222:225], v[80:83]
	v_mfma_f32_16x16x32_bf16 v[124:127], v[132:135], v[188:191], v[124:127]
	v_mfma_f32_16x16x32_bf16 v[92:95], v[140:143], v[188:191], v[92:95]
	v_mfma_f32_16x16x32_bf16 v[120:123], v[132:135], v[196:199], v[120:123]
	v_mfma_f32_16x16x32_bf16 v[88:91], v[140:143], v[196:199], v[88:91]
	v_mfma_f32_16x16x32_bf16 v[116:119], v[132:135], v[218:221], v[116:119]
	v_mfma_f32_16x16x32_bf16 v[84:87], v[140:143], v[218:221], v[84:87]
	v_mfma_f32_16x16x32_bf16 v[112:115], v[132:135], v[226:229], v[112:115]
	v_mfma_f32_16x16x32_bf16 v[80:83], v[140:143], v[226:229], v[80:83]
	v_mfma_f32_16x16x32_bf16 v[60:63], v[164:167], v[184:187], v[60:63]
	v_mfma_f32_16x16x32_bf16 v[28:31], v[176:179], v[184:187], v[28:31]
	v_mfma_f32_16x16x32_bf16 v[56:59], v[164:167], v[192:195], v[56:59]
	v_mfma_f32_16x16x32_bf16 v[24:27], v[176:179], v[192:195], v[24:27]
	v_mfma_f32_16x16x32_bf16 v[52:55], v[164:167], v[200:203], v[52:55]
	v_mfma_f32_16x16x32_bf16 v[20:23], v[176:179], v[200:203], v[20:23]
	v_mfma_f32_16x16x32_bf16 v[48:51], v[164:167], v[222:225], v[48:51]
	v_mfma_f32_16x16x32_bf16 v[16:19], v[176:179], v[222:225], v[16:19]
	v_mfma_f32_16x16x32_bf16 v[60:63], v[168:171], v[188:191], v[60:63]
	v_mfma_f32_16x16x32_bf16 v[28:31], v[180:183], v[188:191], v[28:31]
	v_mfma_f32_16x16x32_bf16 v[56:59], v[168:171], v[196:199], v[56:59]
	v_mfma_f32_16x16x32_bf16 v[24:27], v[180:183], v[196:199], v[24:27]
	v_mfma_f32_16x16x32_bf16 v[52:55], v[168:171], v[218:221], v[52:55]
	v_mfma_f32_16x16x32_bf16 v[20:23], v[180:183], v[218:221], v[20:23]
	v_mfma_f32_16x16x32_bf16 v[48:51], v[168:171], v[226:229], v[48:51]
	v_mfma_f32_16x16x32_bf16 v[16:19], v[180:183], v[226:229], v[16:19]
	s_barrier
	s_add_i32 s53, s53, s36
	v_lshl_add_u64 v[154:155], s[30:31], 0, v[158:159]
	s_mov_b32 m0, s53
	ds_read_b128 v[184:187], v174 offset:16384
	ds_read_b128 v[188:191], v174 offset:17408
	ds_read_b128 v[192:195], v174 offset:18432
	ds_read_b128 v[196:199], v174 offset:19456
	ds_read_b128 v[200:203], v174 offset:20480
	ds_read_b128 v[218:221], v174 offset:21504
	ds_read_b128 v[222:225], v174 offset:22528
	ds_read_b128 v[226:229], v174 offset:23552
	global_load_lds_dwordx4 v[154:155], off
	s_add_i32 m0, s53, 0x2000
	s_add_u32 s54, s30, 0x40000
	v_lshl_add_u64 v[156:157], s[30:31], 0, v[144:145]
	s_addc_u32 s55, s31, 0
	s_add_i32 s53, s56, s36
	global_load_lds_dwordx4 v[156:157], off
	v_lshl_add_u64 v[204:205], s[54:55], 0, v[158:159]
	s_mov_b32 m0, s53
	v_lshl_add_u64 v[212:213], s[34:35], 0, v[146:147]
	global_load_lds_dwordx4 v[204:205], off
	v_lshl_add_u64 v[204:205], s[54:55], 0, v[144:145]
	s_add_i32 m0, s53, 0x2000
	s_nop 0
	global_load_lds_dwordx4 v[204:205], off
	v_lshl_add_u64 v[204:205], s[34:35], 0, v[148:149]
	s_mov_b32 m0, s37
	s_nop 0
	global_load_lds_dwordx4 v[204:205], off
	s_mov_b32 m0, s38
	s_nop 0
	global_load_lds_dwordx4 v[212:213], off
	s_waitcnt vmcnt(8)
	s_waitcnt lgkmcnt(0)
	s_barrier
	s_waitcnt lgkmcnt(0)
	v_mfma_f32_16x16x32_bf16 v[108:111], v[128:131], v[184:187], v[108:111]
	v_mfma_f32_16x16x32_bf16 v[76:79], v[136:139], v[184:187], v[76:79]
	v_mfma_f32_16x16x32_bf16 v[104:107], v[128:131], v[192:195], v[104:107]
	v_mfma_f32_16x16x32_bf16 v[72:75], v[136:139], v[192:195], v[72:75]
	v_mfma_f32_16x16x32_bf16 v[100:103], v[128:131], v[200:203], v[100:103]
	v_mfma_f32_16x16x32_bf16 v[68:71], v[136:139], v[200:203], v[68:71]
	v_mfma_f32_16x16x32_bf16 v[96:99], v[128:131], v[222:225], v[96:99]
	v_mfma_f32_16x16x32_bf16 v[64:67], v[136:139], v[222:225], v[64:67]
	v_mfma_f32_16x16x32_bf16 v[108:111], v[132:135], v[188:191], v[108:111]
	v_mfma_f32_16x16x32_bf16 v[76:79], v[140:143], v[188:191], v[76:79]
	v_mfma_f32_16x16x32_bf16 v[104:107], v[132:135], v[196:199], v[104:107]
	v_mfma_f32_16x16x32_bf16 v[72:75], v[140:143], v[196:199], v[72:75]
	v_mfma_f32_16x16x32_bf16 v[100:103], v[132:135], v[218:221], v[100:103]
	v_mfma_f32_16x16x32_bf16 v[68:71], v[140:143], v[218:221], v[68:71]
	v_mfma_f32_16x16x32_bf16 v[96:99], v[132:135], v[226:229], v[96:99]
	v_mfma_f32_16x16x32_bf16 v[64:67], v[140:143], v[226:229], v[64:67]
	v_mfma_f32_16x16x32_bf16 v[44:47], v[164:167], v[184:187], v[44:47]
	v_mfma_f32_16x16x32_bf16 v[12:15], v[176:179], v[184:187], v[12:15]
	v_mfma_f32_16x16x32_bf16 v[40:43], v[164:167], v[192:195], v[40:43]
	v_mfma_f32_16x16x32_bf16 v[8:11], v[176:179], v[192:195], v[8:11]
	v_mfma_f32_16x16x32_bf16 v[36:39], v[164:167], v[200:203], v[36:39]
	v_mfma_f32_16x16x32_bf16 v[4:7], v[176:179], v[200:203], v[4:7]
	v_mfma_f32_16x16x32_bf16 v[32:35], v[164:167], v[222:225], v[32:35]
	v_mfma_f32_16x16x32_bf16 v[0:3], v[176:179], v[222:225], v[0:3]
	v_mfma_f32_16x16x32_bf16 v[44:47], v[168:171], v[188:191], v[44:47]
	v_mfma_f32_16x16x32_bf16 v[12:15], v[180:183], v[188:191], v[12:15]
	v_mfma_f32_16x16x32_bf16 v[40:43], v[168:171], v[196:199], v[40:43]
	v_mfma_f32_16x16x32_bf16 v[8:11], v[180:183], v[196:199], v[8:11]
	v_mfma_f32_16x16x32_bf16 v[36:39], v[168:171], v[218:221], v[36:39]
	v_mfma_f32_16x16x32_bf16 v[4:7], v[180:183], v[218:221], v[4:7]
	v_mfma_f32_16x16x32_bf16 v[32:35], v[168:171], v[226:229], v[32:35]
	v_mfma_f32_16x16x32_bf16 v[0:3], v[180:183], v[226:229], v[0:3]
	s_barrier
	s_add_i32 s53, 0, 0x18000
	s_add_i32 s54, 0, 0x1c000
	v_add_u32_e32 v140, s53, v173
	v_add_u32_e32 v150, s54, v173
	ds_read_b128 v[128:131], v140
	ds_read_b128 v[132:135], v140 offset:1024
	ds_read_b128 v[136:139], v140 offset:2048
	ds_read_b128 v[140:143], v140 offset:3072
	ds_read_b128 v[164:167], v150
	ds_read_b128 v[168:171], v150 offset:1024
	ds_read_b128 v[176:179], v150 offset:2048
	ds_read_b128 v[180:183], v150 offset:3072
	s_add_u32 s34, s34, 0x40000
	s_addc_u32 s35, s35, 0
	s_mov_b32 m0, s39
	v_lshl_add_u64 v[214:215], s[34:35], 0, v[148:149]
	ds_read_b128 v[184:187], v174 offset:32768
	ds_read_b128 v[188:191], v174 offset:33792
	ds_read_b128 v[192:195], v174 offset:34816
	ds_read_b128 v[196:199], v174 offset:35840
	ds_read_b128 v[200:203], v174 offset:36864
	ds_read_b128 v[218:221], v174 offset:37888
	ds_read_b128 v[222:225], v174 offset:38912
	ds_read_b128 v[226:229], v174 offset:39936
	global_load_lds_dwordx4 v[214:215], off
	v_lshl_add_u64 v[214:215], s[34:35], 0, v[146:147]
	s_mov_b32 m0, s40
	s_nop 0
	global_load_lds_dwordx4 v[214:215], off
	s_waitcnt vmcnt(8)
	s_waitcnt lgkmcnt(0)
	s_barrier
	s_waitcnt lgkmcnt(0)
	v_mfma_f32_16x16x32_bf16 v[124:127], v[128:131], v[184:187], v[124:127]
	v_mfma_f32_16x16x32_bf16 v[92:95], v[136:139], v[184:187], v[92:95]
	v_mfma_f32_16x16x32_bf16 v[120:123], v[128:131], v[192:195], v[120:123]
	v_mfma_f32_16x16x32_bf16 v[88:91], v[136:139], v[192:195], v[88:91]
	v_mfma_f32_16x16x32_bf16 v[116:119], v[128:131], v[200:203], v[116:119]
	v_mfma_f32_16x16x32_bf16 v[84:87], v[136:139], v[200:203], v[84:87]
	v_mfma_f32_16x16x32_bf16 v[112:115], v[128:131], v[222:225], v[112:115]
	v_mfma_f32_16x16x32_bf16 v[80:83], v[136:139], v[222:225], v[80:83]
	v_mfma_f32_16x16x32_bf16 v[124:127], v[132:135], v[188:191], v[124:127]
	v_mfma_f32_16x16x32_bf16 v[92:95], v[140:143], v[188:191], v[92:95]
	v_mfma_f32_16x16x32_bf16 v[120:123], v[132:135], v[196:199], v[120:123]
	v_mfma_f32_16x16x32_bf16 v[88:91], v[140:143], v[196:199], v[88:91]
	v_mfma_f32_16x16x32_bf16 v[116:119], v[132:135], v[218:221], v[116:119]
	v_mfma_f32_16x16x32_bf16 v[84:87], v[140:143], v[218:221], v[84:87]
	v_mfma_f32_16x16x32_bf16 v[112:115], v[132:135], v[226:229], v[112:115]
	v_mfma_f32_16x16x32_bf16 v[80:83], v[140:143], v[226:229], v[80:83]
	v_mfma_f32_16x16x32_bf16 v[60:63], v[164:167], v[184:187], v[60:63]
	v_mfma_f32_16x16x32_bf16 v[28:31], v[176:179], v[184:187], v[28:31]
	v_mfma_f32_16x16x32_bf16 v[56:59], v[164:167], v[192:195], v[56:59]
	v_mfma_f32_16x16x32_bf16 v[24:27], v[176:179], v[192:195], v[24:27]
	v_mfma_f32_16x16x32_bf16 v[52:55], v[164:167], v[200:203], v[52:55]
	v_mfma_f32_16x16x32_bf16 v[20:23], v[176:179], v[200:203], v[20:23]
	v_mfma_f32_16x16x32_bf16 v[48:51], v[164:167], v[222:225], v[48:51]
	v_mfma_f32_16x16x32_bf16 v[16:19], v[176:179], v[222:225], v[16:19]
	v_mfma_f32_16x16x32_bf16 v[60:63], v[168:171], v[188:191], v[60:63]
	v_mfma_f32_16x16x32_bf16 v[28:31], v[180:183], v[188:191], v[28:31]
	v_mfma_f32_16x16x32_bf16 v[56:59], v[168:171], v[196:199], v[56:59]
	v_mfma_f32_16x16x32_bf16 v[24:27], v[180:183], v[196:199], v[24:27]
	v_mfma_f32_16x16x32_bf16 v[52:55], v[168:171], v[218:221], v[52:55]
	v_mfma_f32_16x16x32_bf16 v[20:23], v[180:183], v[218:221], v[20:23]
	v_mfma_f32_16x16x32_bf16 v[48:51], v[168:171], v[226:229], v[48:51]
	v_mfma_f32_16x16x32_bf16 v[16:19], v[180:183], v[226:229], v[16:19]
	s_barrier
	s_add_i32 s34, s53, s36
	v_lshl_add_u64 v[154:155], v[154:155], 0, s[28:29]
	s_mov_b32 m0, s34
	ds_read_b128 v[184:187], v174 offset:49152
	ds_read_b128 v[188:191], v174 offset:50176
	ds_read_b128 v[192:195], v174 offset:51200
	ds_read_b128 v[196:199], v174 offset:52224
	ds_read_b128 v[200:203], v174 offset:53248
	ds_read_b128 v[218:221], v174 offset:54272
	ds_read_b128 v[222:225], v174 offset:55296
	ds_read_b128 v[226:229], v174 offset:56320
	global_load_lds_dwordx4 v[154:155], off
	s_add_i32 m0, s34, 0x2000
	s_add_u32 s30, s30, 0x40080
	v_lshl_add_u64 v[154:155], v[156:157], 0, s[28:29]
	s_addc_u32 s31, s31, 0
	s_add_i32 s34, s54, s36
	global_load_lds_dwordx4 v[154:155], off
	v_lshl_add_u64 v[154:155], s[30:31], 0, v[158:159]
	s_mov_b32 m0, s34
	s_nop 0
	global_load_lds_dwordx4 v[154:155], off
	v_lshl_add_u64 v[154:155], s[30:31], 0, v[144:145]
	s_add_i32 m0, s34, 0x2000
	s_nop 0
	global_load_lds_dwordx4 v[154:155], off
	v_lshl_add_u64 v[154:155], v[204:205], 0, s[28:29]
	s_mov_b32 m0, s43
	s_nop 0
	global_load_lds_dwordx4 v[154:155], off
	v_lshl_add_u64 v[154:155], v[212:213], 0, s[28:29]
	s_mov_b32 m0, s44
	s_nop 0
	global_load_lds_dwordx4 v[154:155], off
	s_waitcnt vmcnt(8)
	s_waitcnt lgkmcnt(0)
	s_barrier
	s_waitcnt lgkmcnt(0)
	v_mfma_f32_16x16x32_bf16 v[108:111], v[128:131], v[184:187], v[108:111]
	v_mfma_f32_16x16x32_bf16 v[76:79], v[136:139], v[184:187], v[76:79]
	v_mfma_f32_16x16x32_bf16 v[104:107], v[128:131], v[192:195], v[104:107]
	v_mfma_f32_16x16x32_bf16 v[72:75], v[136:139], v[192:195], v[72:75]
	v_mfma_f32_16x16x32_bf16 v[100:103], v[128:131], v[200:203], v[100:103]
	v_mfma_f32_16x16x32_bf16 v[68:71], v[136:139], v[200:203], v[68:71]
	v_mfma_f32_16x16x32_bf16 v[96:99], v[128:131], v[222:225], v[96:99]
	v_mfma_f32_16x16x32_bf16 v[64:67], v[136:139], v[222:225], v[64:67]
	v_mfma_f32_16x16x32_bf16 v[108:111], v[132:135], v[188:191], v[108:111]
	v_mfma_f32_16x16x32_bf16 v[76:79], v[140:143], v[188:191], v[76:79]
	v_mfma_f32_16x16x32_bf16 v[104:107], v[132:135], v[196:199], v[104:107]
	v_mfma_f32_16x16x32_bf16 v[72:75], v[140:143], v[196:199], v[72:75]
	v_mfma_f32_16x16x32_bf16 v[100:103], v[132:135], v[218:221], v[100:103]
	v_mfma_f32_16x16x32_bf16 v[68:71], v[140:143], v[218:221], v[68:71]
	v_mfma_f32_16x16x32_bf16 v[96:99], v[132:135], v[226:229], v[96:99]
	v_mfma_f32_16x16x32_bf16 v[64:67], v[140:143], v[226:229], v[64:67]
	v_mfma_f32_16x16x32_bf16 v[44:47], v[164:167], v[184:187], v[44:47]
	v_mfma_f32_16x16x32_bf16 v[12:15], v[176:179], v[184:187], v[12:15]
	v_mfma_f32_16x16x32_bf16 v[40:43], v[164:167], v[192:195], v[40:43]
	v_mfma_f32_16x16x32_bf16 v[8:11], v[176:179], v[192:195], v[8:11]
	v_mfma_f32_16x16x32_bf16 v[36:39], v[164:167], v[200:203], v[36:39]
	v_mfma_f32_16x16x32_bf16 v[4:7], v[176:179], v[200:203], v[4:7]
	v_mfma_f32_16x16x32_bf16 v[32:35], v[164:167], v[222:225], v[32:35]
	v_mfma_f32_16x16x32_bf16 v[0:3], v[176:179], v[222:225], v[0:3]
	v_mfma_f32_16x16x32_bf16 v[44:47], v[168:171], v[188:191], v[44:47]
	v_mfma_f32_16x16x32_bf16 v[12:15], v[180:183], v[188:191], v[12:15]
	v_mfma_f32_16x16x32_bf16 v[40:43], v[168:171], v[196:199], v[40:43]
	v_mfma_f32_16x16x32_bf16 v[8:11], v[180:183], v[196:199], v[8:11]
	v_mfma_f32_16x16x32_bf16 v[36:39], v[168:171], v[218:221], v[36:39]
	v_mfma_f32_16x16x32_bf16 v[4:7], v[180:183], v[218:221], v[4:7]
	v_mfma_f32_16x16x32_bf16 v[32:35], v[168:171], v[226:229], v[32:35]
	v_mfma_f32_16x16x32_bf16 v[0:3], v[180:183], v[226:229], v[0:3]
	s_barrier
	s_add_i32 s52, s52, 2
	s_add_u32 s26, s26, 0x100
	s_addc_u32 s27, s27, 0
	s_add_u32 s50, s50, 0x100
	s_addc_u32 s51, s51, 0
	s_cmp_gt_u32 s52, 13
	s_cbranch_scc0 .LBB0_764
	s_setprio 0
	s_and_b64 vcc, exec, s[16:17]
	s_mov_b32 s49, s57
	s_cbranch_vccz .LBB0_767
	s_barrier

.LBB0_1334:
	s_ashr_i32 s17, s16, 31
	s_lshl_b64 s[18:19], s[16:17], 18
	s_add_u32 s18, s33, s18
	s_addc_u32 s19, s34, s19
	s_and_b64 s[20:21], s[6:7], exec
	s_cselect_b32 s17, s19, s9
	s_cselect_b32 s49, s18, s8
	s_ashr_i32 s15, s14, 31
	s_lshl_b64 s[20:21], s[14:15], 18
	s_add_u32 s20, s35, s20
	s_addc_u32 s21, s36, s21
	s_and_b64 s[24:25], s[6:7], exec
	s_cselect_b32 s15, s21, s23
	s_cselect_b32 s50, s20, s22
	s_add_u32 s8, s8, 0x20080
	s_addc_u32 s9, s9, 0
	s_add_u32 s51, s22, 0x100
	v_mov_b32_e32 v0, 0
	s_addc_u32 s52, s23, 0
	s_mov_b32 s53, -2
	v_mov_b32_e32 v1, v0
	v_mov_b32_e32 v2, v0
	v_mov_b32_e32 v3, v0
	v_mov_b32_e32 v4, v0
	v_mov_b32_e32 v5, v0
	v_mov_b32_e32 v6, v0
	v_mov_b32_e32 v7, v0
	v_mov_b32_e32 v16, v0
	v_mov_b32_e32 v17, v0
	v_mov_b32_e32 v18, v0
	v_mov_b32_e32 v19, v0
	v_mov_b32_e32 v20, v0
	v_mov_b32_e32 v21, v0
	v_mov_b32_e32 v22, v0
	v_mov_b32_e32 v23, v0
	v_mov_b32_e32 v32, v0
	v_mov_b32_e32 v33, v0
	v_mov_b32_e32 v34, v0
	v_mov_b32_e32 v35, v0
	v_mov_b32_e32 v36, v0
	v_mov_b32_e32 v37, v0
	v_mov_b32_e32 v38, v0
	v_mov_b32_e32 v39, v0
	v_mov_b32_e32 v48, v0
	v_mov_b32_e32 v49, v0
	v_mov_b32_e32 v50, v0
	v_mov_b32_e32 v51, v0
	v_mov_b32_e32 v52, v0
	v_mov_b32_e32 v53, v0
	v_mov_b32_e32 v54, v0
	v_mov_b32_e32 v55, v0
	v_mov_b32_e32 v8, v0
	v_mov_b32_e32 v9, v0
	v_mov_b32_e32 v10, v0
	v_mov_b32_e32 v11, v0
	v_mov_b32_e32 v12, v0
	v_mov_b32_e32 v13, v0
	v_mov_b32_e32 v14, v0
	v_mov_b32_e32 v15, v0
	v_mov_b32_e32 v24, v0
	v_mov_b32_e32 v25, v0
	v_mov_b32_e32 v26, v0
	v_mov_b32_e32 v27, v0
	v_mov_b32_e32 v28, v0
	v_mov_b32_e32 v29, v0
	v_mov_b32_e32 v30, v0
	v_mov_b32_e32 v31, v0
	v_mov_b32_e32 v40, v0
	v_mov_b32_e32 v41, v0
	v_mov_b32_e32 v42, v0
	v_mov_b32_e32 v43, v0
	v_mov_b32_e32 v44, v0
	v_mov_b32_e32 v45, v0
	v_mov_b32_e32 v46, v0
	v_mov_b32_e32 v47, v0
	v_mov_b32_e32 v56, v0
	v_mov_b32_e32 v57, v0
	v_mov_b32_e32 v58, v0
	v_mov_b32_e32 v59, v0
	v_mov_b32_e32 v60, v0
	v_mov_b32_e32 v61, v0
	v_mov_b32_e32 v62, v0
	v_mov_b32_e32 v63, v0
	v_mov_b32_e32 v64, v0
	v_mov_b32_e32 v65, v0
	v_mov_b32_e32 v66, v0
	v_mov_b32_e32 v67, v0
	v_mov_b32_e32 v68, v0
	v_mov_b32_e32 v69, v0
	v_mov_b32_e32 v70, v0
	v_mov_b32_e32 v71, v0
	v_mov_b32_e32 v80, v0
	v_mov_b32_e32 v81, v0
	v_mov_b32_e32 v82, v0
	v_mov_b32_e32 v83, v0
	v_mov_b32_e32 v84, v0
	v_mov_b32_e32 v85, v0
	v_mov_b32_e32 v86, v0
	v_mov_b32_e32 v87, v0
	v_mov_b32_e32 v96, v0
	v_mov_b32_e32 v97, v0
	v_mov_b32_e32 v98, v0
	v_mov_b32_e32 v99, v0
	v_mov_b32_e32 v100, v0
	v_mov_b32_e32 v101, v0
	v_mov_b32_e32 v102, v0
	v_mov_b32_e32 v103, v0
	v_mov_b32_e32 v112, v0
	v_mov_b32_e32 v113, v0
	v_mov_b32_e32 v114, v0
	v_mov_b32_e32 v115, v0
	v_mov_b32_e32 v116, v0
	v_mov_b32_e32 v117, v0
	v_mov_b32_e32 v118, v0
	v_mov_b32_e32 v119, v0
	v_mov_b32_e32 v72, v0
	v_mov_b32_e32 v73, v0
	v_mov_b32_e32 v74, v0
	v_mov_b32_e32 v75, v0
	v_mov_b32_e32 v76, v0
	v_mov_b32_e32 v77, v0
	v_mov_b32_e32 v78, v0
	v_mov_b32_e32 v79, v0
	v_mov_b32_e32 v88, v0
	v_mov_b32_e32 v89, v0
	v_mov_b32_e32 v90, v0
	v_mov_b32_e32 v91, v0
	v_mov_b32_e32 v92, v0
	v_mov_b32_e32 v93, v0
	v_mov_b32_e32 v94, v0
	v_mov_b32_e32 v95, v0
	v_mov_b32_e32 v104, v0
	v_mov_b32_e32 v105, v0
	v_mov_b32_e32 v106, v0
	v_mov_b32_e32 v107, v0
	v_mov_b32_e32 v108, v0
	v_mov_b32_e32 v109, v0
	v_mov_b32_e32 v110, v0
	v_mov_b32_e32 v111, v0
	v_mov_b32_e32 v120, v0
	v_mov_b32_e32 v121, v0
	v_mov_b32_e32 v122, v0
	v_mov_b32_e32 v123, v0
	v_mov_b32_e32 v124, v0
	v_mov_b32_e32 v125, v0
	v_mov_b32_e32 v126, v0
	v_mov_b32_e32 v127, v0
	v_readfirstlane_b32 s100, v206
	s_nop 0
	s_cmp_lt_u32 s100, 0x100
	s_cbranch_scc1 .Lprio_skip_4
	s_setprio 1

.LBB0_1335:
	s_add_u32 s22, s8, 0xfffe0080
	s_addc_u32 s23, s9, -1
	s_add_i32 s54, 0, 0x10000
	s_cmp_eq_u32 s53, 4
	s_cselect_b32 s25, s17, s23
	s_cselect_b32 s24, s49, s22
	v_add_u32_e32 v146, s54, v158
	s_cselect_b32 s23, s15, s52
	s_cselect_b32 s22, s50, s51
	s_add_i32 s56, 0, 0x14000
	ds_read_b128 v[138:141], v146
	ds_read_b128 v[142:145], v146 offset:1024
	ds_read_b128 v[154:157], v146 offset:2048
	ds_read_b128 v[160:163], v146 offset:3072
	v_add_u32_e32 v146, s56, v158
	ds_read_b128 v[164:167], v146
	ds_read_b128 v[168:171], v146 offset:1024
	ds_read_b128 v[172:175], v146 offset:2048
	ds_read_b128 v[176:179], v146 offset:3072
	v_lshl_add_u64 v[146:147], s[8:9], 0, v[134:135]
	s_add_i32 m0, s38, 0xc000
	ds_read_b128 v[180:183], v159
	ds_read_b128 v[184:187], v159 offset:1024
	ds_read_b128 v[188:191], v159 offset:2048
	ds_read_b128 v[192:195], v159 offset:3072
	ds_read_b128 v[196:199], v159 offset:4096
	ds_read_b128 v[200:203], v159 offset:5120
	ds_read_b128 v[212:215], v159 offset:6144
	ds_read_b128 v[220:223], v159 offset:7168
	global_load_lds_dwordx4 v[146:147], off
	v_lshl_add_u64 v[146:147], s[8:9], 0, v[136:137]
	s_add_i32 m0, s38, 0xe000
	s_nop 0
	global_load_lds_dwordx4 v[146:147], off
	s_waitcnt vmcnt(8)
	s_waitcnt lgkmcnt(0)
	s_barrier
	s_waitcnt lgkmcnt(0)
	v_mfma_f32_16x16x32_bf16 v[124:127], v[138:141], v[180:183], v[124:127]
	v_mfma_f32_16x16x32_bf16 v[120:123], v[154:157], v[180:183], v[120:123]
	v_mfma_f32_16x16x32_bf16 v[108:111], v[138:141], v[188:191], v[108:111]
	v_mfma_f32_16x16x32_bf16 v[104:107], v[154:157], v[188:191], v[104:107]
	v_mfma_f32_16x16x32_bf16 v[92:95], v[138:141], v[196:199], v[92:95]
	v_mfma_f32_16x16x32_bf16 v[88:91], v[154:157], v[196:199], v[88:91]
	v_mfma_f32_16x16x32_bf16 v[76:79], v[138:141], v[212:215], v[76:79]
	v_mfma_f32_16x16x32_bf16 v[72:75], v[154:157], v[212:215], v[72:75]
	v_mfma_f32_16x16x32_bf16 v[124:127], v[142:145], v[184:187], v[124:127]
	v_mfma_f32_16x16x32_bf16 v[120:123], v[160:163], v[184:187], v[120:123]
	v_mfma_f32_16x16x32_bf16 v[108:111], v[142:145], v[192:195], v[108:111]
	v_mfma_f32_16x16x32_bf16 v[104:107], v[160:163], v[192:195], v[104:107]
	v_mfma_f32_16x16x32_bf16 v[92:95], v[142:145], v[200:203], v[92:95]
	v_mfma_f32_16x16x32_bf16 v[88:91], v[160:163], v[200:203], v[88:91]
	v_mfma_f32_16x16x32_bf16 v[76:79], v[142:145], v[220:223], v[76:79]
	v_mfma_f32_16x16x32_bf16 v[72:75], v[160:163], v[220:223], v[72:75]
	v_mfma_f32_16x16x32_bf16 v[116:119], v[164:167], v[180:183], v[116:119]
	v_mfma_f32_16x16x32_bf16 v[112:115], v[172:175], v[180:183], v[112:115]
	v_mfma_f32_16x16x32_bf16 v[100:103], v[164:167], v[188:191], v[100:103]
	v_mfma_f32_16x16x32_bf16 v[96:99], v[172:175], v[188:191], v[96:99]
	v_mfma_f32_16x16x32_bf16 v[84:87], v[164:167], v[196:199], v[84:87]
	v_mfma_f32_16x16x32_bf16 v[80:83], v[172:175], v[196:199], v[80:83]
	v_mfma_f32_16x16x32_bf16 v[68:71], v[164:167], v[212:215], v[68:71]
	v_mfma_f32_16x16x32_bf16 v[64:67], v[172:175], v[212:215], v[64:67]
	v_mfma_f32_16x16x32_bf16 v[116:119], v[168:171], v[184:187], v[116:119]
	v_mfma_f32_16x16x32_bf16 v[112:115], v[176:179], v[184:187], v[112:115]
	v_mfma_f32_16x16x32_bf16 v[100:103], v[168:171], v[192:195], v[100:103]
	v_mfma_f32_16x16x32_bf16 v[96:99], v[176:179], v[192:195], v[96:99]
	v_mfma_f32_16x16x32_bf16 v[84:87], v[168:171], v[200:203], v[84:87]
	v_mfma_f32_16x16x32_bf16 v[80:83], v[176:179], v[200:203], v[80:83]
	v_mfma_f32_16x16x32_bf16 v[68:71], v[168:171], v[220:223], v[68:71]
	v_mfma_f32_16x16x32_bf16 v[64:67], v[176:179], v[220:223], v[64:67]
	s_barrier
	s_add_i32 s54, s54, s37
	v_lshl_add_u64 v[146:147], s[22:23], 0, v[148:149]
	s_mov_b32 m0, s54
	ds_read_b128 v[180:183], v159 offset:16384
	ds_read_b128 v[184:187], v159 offset:17408
	ds_read_b128 v[188:191], v159 offset:18432
	ds_read_b128 v[192:195], v159 offset:19456
	ds_read_b128 v[196:199], v159 offset:20480
	ds_read_b128 v[200:203], v159 offset:21504
	ds_read_b128 v[212:215], v159 offset:22528
	ds_read_b128 v[220:223], v159 offset:23552
	global_load_lds_dwordx4 v[146:147], off
	s_add_i32 m0, s54, 0x2000
	s_add_u32 s54, s22, 0x20000
	v_lshl_add_u64 v[150:151], s[22:23], 0, v[128:129]
	s_addc_u32 s55, s23, 0
	s_add_i32 s56, s56, s37
	global_load_lds_dwordx4 v[150:151], off
	v_lshl_add_u64 v[152:153], s[54:55], 0, v[148:149]
	s_mov_b32 m0, s56
	v_lshl_add_u64 v[204:205], s[24:25], 0, v[130:131]
	global_load_lds_dwordx4 v[152:153], off
	v_lshl_add_u64 v[152:153], s[54:55], 0, v[128:129]
	s_add_i32 m0, s56, 0x2000
	s_nop 0
	global_load_lds_dwordx4 v[152:153], off
	v_lshl_add_u64 v[152:153], s[24:25], 0, v[132:133]
	s_mov_b32 m0, s38
	s_nop 0
	global_load_lds_dwordx4 v[152:153], off
	s_mov_b32 m0, s39
	s_nop 0
	global_load_lds_dwordx4 v[204:205], off
	s_waitcnt vmcnt(8)
	s_waitcnt lgkmcnt(0)
	s_barrier
	s_waitcnt lgkmcnt(0)
	v_mfma_f32_16x16x32_bf16 v[60:63], v[138:141], v[180:183], v[60:63]
	v_mfma_f32_16x16x32_bf16 v[56:59], v[154:157], v[180:183], v[56:59]
	v_mfma_f32_16x16x32_bf16 v[44:47], v[138:141], v[188:191], v[44:47]
	v_mfma_f32_16x16x32_bf16 v[40:43], v[154:157], v[188:191], v[40:43]
	v_mfma_f32_16x16x32_bf16 v[28:31], v[138:141], v[196:199], v[28:31]
	v_mfma_f32_16x16x32_bf16 v[24:27], v[154:157], v[196:199], v[24:27]
	v_mfma_f32_16x16x32_bf16 v[12:15], v[138:141], v[212:215], v[12:15]
	v_mfma_f32_16x16x32_bf16 v[8:11], v[154:157], v[212:215], v[8:11]
	v_mfma_f32_16x16x32_bf16 v[60:63], v[142:145], v[184:187], v[60:63]
	v_mfma_f32_16x16x32_bf16 v[56:59], v[160:163], v[184:187], v[56:59]
	v_mfma_f32_16x16x32_bf16 v[44:47], v[142:145], v[192:195], v[44:47]
	v_mfma_f32_16x16x32_bf16 v[40:43], v[160:163], v[192:195], v[40:43]
	v_mfma_f32_16x16x32_bf16 v[28:31], v[142:145], v[200:203], v[28:31]
	v_mfma_f32_16x16x32_bf16 v[24:27], v[160:163], v[200:203], v[24:27]
	v_mfma_f32_16x16x32_bf16 v[12:15], v[142:145], v[220:223], v[12:15]
	v_mfma_f32_16x16x32_bf16 v[8:11], v[160:163], v[220:223], v[8:11]
	v_mfma_f32_16x16x32_bf16 v[52:55], v[164:167], v[180:183], v[52:55]
	v_mfma_f32_16x16x32_bf16 v[48:51], v[172:175], v[180:183], v[48:51]
	v_mfma_f32_16x16x32_bf16 v[36:39], v[164:167], v[188:191], v[36:39]
	v_mfma_f32_16x16x32_bf16 v[32:35], v[172:175], v[188:191], v[32:35]
	v_mfma_f32_16x16x32_bf16 v[20:23], v[164:167], v[196:199], v[20:23]
	v_mfma_f32_16x16x32_bf16 v[16:19], v[172:175], v[196:199], v[16:19]
	v_mfma_f32_16x16x32_bf16 v[4:7], v[164:167], v[212:215], v[4:7]
	v_mfma_f32_16x16x32_bf16 v[0:3], v[172:175], v[212:215], v[0:3]
	v_mfma_f32_16x16x32_bf16 v[52:55], v[168:171], v[184:187], v[52:55]
	v_mfma_f32_16x16x32_bf16 v[48:51], v[176:179], v[184:187], v[48:51]
	v_mfma_f32_16x16x32_bf16 v[36:39], v[168:171], v[192:195], v[36:39]
	v_mfma_f32_16x16x32_bf16 v[32:35], v[176:179], v[192:195], v[32:35]
	v_mfma_f32_16x16x32_bf16 v[20:23], v[168:171], v[200:203], v[20:23]
	v_mfma_f32_16x16x32_bf16 v[16:19], v[176:179], v[200:203], v[16:19]
	v_mfma_f32_16x16x32_bf16 v[4:7], v[168:171], v[220:223], v[4:7]
	v_mfma_f32_16x16x32_bf16 v[0:3], v[176:179], v[220:223], v[0:3]
	s_barrier
	s_add_i32 s54, 0, 0x18000
	s_add_i32 s55, 0, 0x1c000
	v_add_u32_e32 v160, s54, v158
	v_add_u32_e32 v176, s55, v158
	ds_read_b128 v[138:141], v160
	ds_read_b128 v[142:145], v160 offset:1024
	ds_read_b128 v[154:157], v160 offset:2048
	ds_read_b128 v[160:163], v160 offset:3072
	ds_read_b128 v[164:167], v176
	ds_read_b128 v[168:171], v176 offset:1024
	ds_read_b128 v[172:175], v176 offset:2048
	ds_read_b128 v[176:179], v176 offset:3072
	s_add_u32 s24, s24, 0x20000
	s_addc_u32 s25, s25, 0
	s_mov_b32 m0, s40
	v_lshl_add_u64 v[208:209], s[24:25], 0, v[132:133]
	ds_read_b128 v[180:183], v159 offset:32768
	ds_read_b128 v[184:187], v159 offset:33792
	ds_read_b128 v[188:191], v159 offset:34816
	ds_read_b128 v[192:195], v159 offset:35840
	ds_read_b128 v[196:199], v159 offset:36864
	ds_read_b128 v[200:203], v159 offset:37888
	ds_read_b128 v[212:215], v159 offset:38912
	ds_read_b128 v[220:223], v159 offset:39936
	global_load_lds_dwordx4 v[208:209], off
	v_lshl_add_u64 v[208:209], s[24:25], 0, v[130:131]
	s_mov_b32 m0, s41
	s_nop 0
	global_load_lds_dwordx4 v[208:209], off
	s_waitcnt vmcnt(8)
	s_waitcnt lgkmcnt(0)
	s_barrier
	s_waitcnt lgkmcnt(0)
	v_mfma_f32_16x16x32_bf16 v[124:127], v[138:141], v[180:183], v[124:127]
	v_mfma_f32_16x16x32_bf16 v[120:123], v[154:157], v[180:183], v[120:123]
	v_mfma_f32_16x16x32_bf16 v[108:111], v[138:141], v[188:191], v[108:111]
	v_mfma_f32_16x16x32_bf16 v[104:107], v[154:157], v[188:191], v[104:107]
	v_mfma_f32_16x16x32_bf16 v[92:95], v[138:141], v[196:199], v[92:95]
	v_mfma_f32_16x16x32_bf16 v[88:91], v[154:157], v[196:199], v[88:91]
	v_mfma_f32_16x16x32_bf16 v[76:79], v[138:141], v[212:215], v[76:79]
	v_mfma_f32_16x16x32_bf16 v[72:75], v[154:157], v[212:215], v[72:75]
	v_mfma_f32_16x16x32_bf16 v[124:127], v[142:145], v[184:187], v[124:127]
	v_mfma_f32_16x16x32_bf16 v[120:123], v[160:163], v[184:187], v[120:123]
	v_mfma_f32_16x16x32_bf16 v[108:111], v[142:145], v[192:195], v[108:111]
	v_mfma_f32_16x16x32_bf16 v[104:107], v[160:163], v[192:195], v[104:107]
	v_mfma_f32_16x16x32_bf16 v[92:95], v[142:145], v[200:203], v[92:95]
	v_mfma_f32_16x16x32_bf16 v[88:91], v[160:163], v[200:203], v[88:91]
	v_mfma_f32_16x16x32_bf16 v[76:79], v[142:145], v[220:223], v[76:79]
	v_mfma_f32_16x16x32_bf16 v[72:75], v[160:163], v[220:223], v[72:75]
	v_mfma_f32_16x16x32_bf16 v[116:119], v[164:167], v[180:183], v[116:119]
	v_mfma_f32_16x16x32_bf16 v[112:115], v[172:175], v[180:183], v[112:115]
	v_mfma_f32_16x16x32_bf16 v[100:103], v[164:167], v[188:191], v[100:103]
	v_mfma_f32_16x16x32_bf16 v[96:99], v[172:175], v[188:191], v[96:99]
	v_mfma_f32_16x16x32_bf16 v[84:87], v[164:167], v[196:199], v[84:87]
	v_mfma_f32_16x16x32_bf16 v[80:83], v[172:175], v[196:199], v[80:83]
	v_mfma_f32_16x16x32_bf16 v[68:71], v[164:167], v[212:215], v[68:71]
	v_mfma_f32_16x16x32_bf16 v[64:67], v[172:175], v[212:215], v[64:67]
	v_mfma_f32_16x16x32_bf16 v[116:119], v[168:171], v[184:187], v[116:119]
	v_mfma_f32_16x16x32_bf16 v[112:115], v[176:179], v[184:187], v[112:115]
	v_mfma_f32_16x16x32_bf16 v[100:103], v[168:171], v[192:195], v[100:103]
	v_mfma_f32_16x16x32_bf16 v[96:99], v[176:179], v[192:195], v[96:99]
	v_mfma_f32_16x16x32_bf16 v[84:87], v[168:171], v[200:203], v[84:87]
	v_mfma_f32_16x16x32_bf16 v[80:83], v[176:179], v[200:203], v[80:83]
	v_mfma_f32_16x16x32_bf16 v[68:71], v[168:171], v[220:223], v[68:71]
	v_mfma_f32_16x16x32_bf16 v[64:67], v[176:179], v[220:223], v[64:67]
	s_barrier
	s_add_i32 s24, s54, s37
	v_lshl_add_u64 v[146:147], v[146:147], 0, s[28:29]
	s_mov_b32 m0, s24
	ds_read_b128 v[180:183], v159 offset:49152
	ds_read_b128 v[184:187], v159 offset:50176
	ds_read_b128 v[188:191], v159 offset:51200
	ds_read_b128 v[192:195], v159 offset:52224
	ds_read_b128 v[196:199], v159 offset:53248
	ds_read_b128 v[200:203], v159 offset:54272
	ds_read_b128 v[212:215], v159 offset:55296
	ds_read_b128 v[220:223], v159 offset:56320
	global_load_lds_dwordx4 v[146:147], off
	s_add_i32 m0, s24, 0x2000
	s_add_u32 s22, s22, 0x20080
	v_lshl_add_u64 v[146:147], v[150:151], 0, s[28:29]
	s_addc_u32 s23, s23, 0
	s_add_i32 s24, s55, s37
	global_load_lds_dwordx4 v[146:147], off
	v_lshl_add_u64 v[146:147], s[22:23], 0, v[148:149]
	s_mov_b32 m0, s24
	s_nop 0
	global_load_lds_dwordx4 v[146:147], off
	v_lshl_add_u64 v[146:147], s[22:23], 0, v[128:129]
	s_add_i32 m0, s24, 0x2000
	s_nop 0
	global_load_lds_dwordx4 v[146:147], off
	v_lshl_add_u64 v[146:147], v[152:153], 0, s[28:29]
	s_mov_b32 m0, s45
	s_nop 0
	global_load_lds_dwordx4 v[146:147], off
	v_lshl_add_u64 v[146:147], v[204:205], 0, s[28:29]
	s_mov_b32 m0, s46
	s_nop 0
	global_load_lds_dwordx4 v[146:147], off
	s_waitcnt vmcnt(8)
	s_waitcnt lgkmcnt(0)
	s_barrier
	s_waitcnt lgkmcnt(0)
	v_mfma_f32_16x16x32_bf16 v[60:63], v[138:141], v[180:183], v[60:63]
	v_mfma_f32_16x16x32_bf16 v[56:59], v[154:157], v[180:183], v[56:59]
	v_mfma_f32_16x16x32_bf16 v[44:47], v[138:141], v[188:191], v[44:47]
	v_mfma_f32_16x16x32_bf16 v[40:43], v[154:157], v[188:191], v[40:43]
	v_mfma_f32_16x16x32_bf16 v[28:31], v[138:141], v[196:199], v[28:31]
	v_mfma_f32_16x16x32_bf16 v[24:27], v[154:157], v[196:199], v[24:27]
	v_mfma_f32_16x16x32_bf16 v[12:15], v[138:141], v[212:215], v[12:15]
	v_mfma_f32_16x16x32_bf16 v[8:11], v[154:157], v[212:215], v[8:11]
	v_mfma_f32_16x16x32_bf16 v[60:63], v[142:145], v[184:187], v[60:63]
	v_mfma_f32_16x16x32_bf16 v[56:59], v[160:163], v[184:187], v[56:59]
	v_mfma_f32_16x16x32_bf16 v[44:47], v[142:145], v[192:195], v[44:47]
	v_mfma_f32_16x16x32_bf16 v[40:43], v[160:163], v[192:195], v[40:43]
	v_mfma_f32_16x16x32_bf16 v[28:31], v[142:145], v[200:203], v[28:31]
	v_mfma_f32_16x16x32_bf16 v[24:27], v[160:163], v[200:203], v[24:27]
	v_mfma_f32_16x16x32_bf16 v[12:15], v[142:145], v[220:223], v[12:15]
	v_mfma_f32_16x16x32_bf16 v[8:11], v[160:163], v[220:223], v[8:11]
	v_mfma_f32_16x16x32_bf16 v[52:55], v[164:167], v[180:183], v[52:55]
	v_mfma_f32_16x16x32_bf16 v[48:51], v[172:175], v[180:183], v[48:51]
	v_mfma_f32_16x16x32_bf16 v[36:39], v[164:167], v[188:191], v[36:39]
	v_mfma_f32_16x16x32_bf16 v[32:35], v[172:175], v[188:191], v[32:35]
	v_mfma_f32_16x16x32_bf16 v[20:23], v[164:167], v[196:199], v[20:23]
	v_mfma_f32_16x16x32_bf16 v[16:19], v[172:175], v[196:199], v[16:19]
	v_mfma_f32_16x16x32_bf16 v[4:7], v[164:167], v[212:215], v[4:7]
	v_mfma_f32_16x16x32_bf16 v[0:3], v[172:175], v[212:215], v[0:3]
	v_mfma_f32_16x16x32_bf16 v[52:55], v[168:171], v[184:187], v[52:55]
	v_mfma_f32_16x16x32_bf16 v[48:51], v[176:179], v[184:187], v[48:51]
	v_mfma_f32_16x16x32_bf16 v[36:39], v[168:171], v[192:195], v[36:39]
	v_mfma_f32_16x16x32_bf16 v[32:35], v[176:179], v[192:195], v[32:35]
	v_mfma_f32_16x16x32_bf16 v[20:23], v[168:171], v[200:203], v[20:23]
	v_mfma_f32_16x16x32_bf16 v[16:19], v[176:179], v[200:203], v[16:19]
	v_mfma_f32_16x16x32_bf16 v[4:7], v[168:171], v[220:223], v[4:7]
	v_mfma_f32_16x16x32_bf16 v[0:3], v[176:179], v[220:223], v[0:3]
	s_barrier
	s_add_i32 s53, s53, 2
	s_add_u32 s8, s8, 0x100
	s_addc_u32 s9, s9, 0
	s_add_u32 s51, s51, 0x100
	s_addc_u32 s52, s52, 0
	s_cmp_gt_u32 s53, 5
	s_cbranch_scc0 .LBB0_1335
	s_setprio 0
	s_and_b64 vcc, exec, s[12:13]
	s_cbranch_vccz .LBB0_1338
	s_barrier

.LBB0_1437:
	s_ashr_i32 s13, s12, 31
	s_lshl_b64 s[14:15], s[12:13], 19
	s_add_u32 s14, s24, s14
	s_addc_u32 s15, s25, s15
	s_and_b64 s[16:17], s[4:5], exec
	s_cselect_b32 s13, s15, s19
	s_cselect_b32 s44, s14, s18
	s_ashr_i32 s11, s10, 31
	s_lshl_b64 s[16:17], s[10:11], 19
	s_add_u32 s16, s26, s16
	s_addc_u32 s17, s27, s17
	s_and_b64 s[22:23], s[4:5], exec
	s_cselect_b32 s11, s17, s21
	s_cselect_b32 s45, s16, s20
	s_add_u32 s18, s18, 0x40080
	s_addc_u32 s19, s19, 0
	s_add_u32 s46, s20, 0x100
	v_mov_b32_e32 v0, 0
	s_mov_b32 s53, s49
	s_addc_u32 s47, s21, 0
	s_mov_b32 s48, -2
	v_mov_b32_e32 v1, v0
	v_mov_b32_e32 v2, v0
	v_mov_b32_e32 v3, v0
	v_mov_b32_e32 v4, v0
	v_mov_b32_e32 v5, v0
	v_mov_b32_e32 v6, v0
	v_mov_b32_e32 v7, v0
	v_mov_b32_e32 v16, v0
	v_mov_b32_e32 v17, v0
	v_mov_b32_e32 v18, v0
	v_mov_b32_e32 v19, v0
	v_mov_b32_e32 v20, v0
	v_mov_b32_e32 v21, v0
	v_mov_b32_e32 v22, v0
	v_mov_b32_e32 v23, v0
	v_mov_b32_e32 v32, v0
	v_mov_b32_e32 v33, v0
	v_mov_b32_e32 v34, v0
	v_mov_b32_e32 v35, v0
	v_mov_b32_e32 v36, v0
	v_mov_b32_e32 v37, v0
	v_mov_b32_e32 v38, v0
	v_mov_b32_e32 v39, v0
	v_mov_b32_e32 v48, v0
	v_mov_b32_e32 v49, v0
	v_mov_b32_e32 v50, v0
	v_mov_b32_e32 v51, v0
	v_mov_b32_e32 v52, v0
	v_mov_b32_e32 v53, v0
	v_mov_b32_e32 v54, v0
	v_mov_b32_e32 v55, v0
	v_mov_b32_e32 v8, v0
	v_mov_b32_e32 v9, v0
	v_mov_b32_e32 v10, v0
	v_mov_b32_e32 v11, v0
	v_mov_b32_e32 v12, v0
	v_mov_b32_e32 v13, v0
	v_mov_b32_e32 v14, v0
	v_mov_b32_e32 v15, v0
	v_mov_b32_e32 v24, v0
	v_mov_b32_e32 v25, v0
	v_mov_b32_e32 v26, v0
	v_mov_b32_e32 v27, v0
	v_mov_b32_e32 v28, v0
	v_mov_b32_e32 v29, v0
	v_mov_b32_e32 v30, v0
	v_mov_b32_e32 v31, v0
	v_mov_b32_e32 v40, v0
	v_mov_b32_e32 v41, v0
	v_mov_b32_e32 v42, v0
	v_mov_b32_e32 v43, v0
	v_mov_b32_e32 v44, v0
	v_mov_b32_e32 v45, v0
	v_mov_b32_e32 v46, v0
	v_mov_b32_e32 v47, v0
	v_mov_b32_e32 v56, v0
	v_mov_b32_e32 v57, v0
	v_mov_b32_e32 v58, v0
	v_mov_b32_e32 v59, v0
	v_mov_b32_e32 v60, v0
	v_mov_b32_e32 v61, v0
	v_mov_b32_e32 v62, v0
	v_mov_b32_e32 v63, v0
	v_mov_b32_e32 v64, v0
	v_mov_b32_e32 v65, v0
	v_mov_b32_e32 v66, v0
	v_mov_b32_e32 v67, v0
	v_mov_b32_e32 v68, v0
	v_mov_b32_e32 v69, v0
	v_mov_b32_e32 v70, v0
	v_mov_b32_e32 v71, v0
	v_mov_b32_e32 v80, v0
	v_mov_b32_e32 v81, v0
	v_mov_b32_e32 v82, v0
	v_mov_b32_e32 v83, v0
	v_mov_b32_e32 v84, v0
	v_mov_b32_e32 v85, v0
	v_mov_b32_e32 v86, v0
	v_mov_b32_e32 v87, v0
	v_mov_b32_e32 v96, v0
	v_mov_b32_e32 v97, v0
	v_mov_b32_e32 v98, v0
	v_mov_b32_e32 v99, v0
	v_mov_b32_e32 v100, v0
	v_mov_b32_e32 v101, v0
	v_mov_b32_e32 v102, v0
	v_mov_b32_e32 v103, v0
	v_mov_b32_e32 v112, v0
	v_mov_b32_e32 v113, v0
	v_mov_b32_e32 v114, v0
	v_mov_b32_e32 v115, v0
	v_mov_b32_e32 v116, v0
	v_mov_b32_e32 v117, v0
	v_mov_b32_e32 v118, v0
	v_mov_b32_e32 v119, v0
	v_mov_b32_e32 v72, v0
	v_mov_b32_e32 v73, v0
	v_mov_b32_e32 v74, v0
	v_mov_b32_e32 v75, v0
	v_mov_b32_e32 v76, v0
	v_mov_b32_e32 v77, v0
	v_mov_b32_e32 v78, v0
	v_mov_b32_e32 v79, v0
	v_mov_b32_e32 v88, v0
	v_mov_b32_e32 v89, v0
	v_mov_b32_e32 v90, v0
	v_mov_b32_e32 v91, v0
	v_mov_b32_e32 v92, v0
	v_mov_b32_e32 v93, v0
	v_mov_b32_e32 v94, v0
	v_mov_b32_e32 v95, v0
	v_mov_b32_e32 v104, v0
	v_mov_b32_e32 v105, v0
	v_mov_b32_e32 v106, v0
	v_mov_b32_e32 v107, v0
	v_mov_b32_e32 v108, v0
	v_mov_b32_e32 v109, v0
	v_mov_b32_e32 v110, v0
	v_mov_b32_e32 v111, v0
	v_mov_b32_e32 v120, v0
	v_mov_b32_e32 v121, v0
	v_mov_b32_e32 v122, v0
	v_mov_b32_e32 v123, v0
	v_mov_b32_e32 v124, v0
	v_mov_b32_e32 v125, v0
	v_mov_b32_e32 v126, v0
	v_mov_b32_e32 v127, v0
	v_readfirstlane_b32 s100, v206
	s_nop 0
	s_cmp_lt_u32 s100, 0x100
	s_cbranch_scc1 .Lprio_skip_5
	s_setprio 1

.LBB0_1438:
	s_add_u32 s20, s18, 0xfffc0080
	s_addc_u32 s21, s19, -1
	s_add_i32 s49, 0, 0x10000
	s_cmp_eq_u32 s48, 12
	s_cselect_b32 s23, s13, s21
	s_cselect_b32 s22, s44, s20
	v_add_u32_e32 v142, s49, v144
	s_cselect_b32 s21, s11, s47
	s_cselect_b32 s20, s45, s46
	s_add_i32 s52, 0, 0x14000
	ds_read_b128 v[138:141], v142
	ds_read_b128 v[154:157], v142 offset:1024
	ds_read_b128 v[158:161], v142 offset:2048
	ds_read_b128 v[162:165], v142 offset:3072
	v_add_u32_e32 v142, s52, v144
	ds_read_b128 v[166:169], v142
	ds_read_b128 v[170:173], v142 offset:1024
	ds_read_b128 v[174:177], v142 offset:2048
	ds_read_b128 v[178:181], v142 offset:3072
	v_lshl_add_u64 v[142:143], s[18:19], 0, v[134:135]
	s_add_i32 m0, s31, 0xc000
	ds_read_b128 v[182:185], v145
	ds_read_b128 v[186:189], v145 offset:1024
	ds_read_b128 v[190:193], v145 offset:2048
	ds_read_b128 v[194:197], v145 offset:3072
	ds_read_b128 v[198:201], v145 offset:4096
	ds_read_b128 v[202:205], v145 offset:5120
	ds_read_b128 v[212:215], v145 offset:6144
	ds_read_b128 v[220:223], v145 offset:7168
	global_load_lds_dwordx4 v[142:143], off
	v_lshl_add_u64 v[142:143], s[18:19], 0, v[136:137]
	s_add_i32 m0, s31, 0xe000
	s_nop 0
	global_load_lds_dwordx4 v[142:143], off
	s_waitcnt vmcnt(8)
	s_waitcnt lgkmcnt(0)
	s_barrier
	s_waitcnt lgkmcnt(0)
	v_mfma_f32_16x16x32_bf16 v[124:127], v[138:141], v[182:185], v[124:127]
	v_mfma_f32_16x16x32_bf16 v[120:123], v[158:161], v[182:185], v[120:123]
	v_mfma_f32_16x16x32_bf16 v[108:111], v[138:141], v[190:193], v[108:111]
	v_mfma_f32_16x16x32_bf16 v[104:107], v[158:161], v[190:193], v[104:107]
	v_mfma_f32_16x16x32_bf16 v[92:95], v[138:141], v[198:201], v[92:95]
	v_mfma_f32_16x16x32_bf16 v[88:91], v[158:161], v[198:201], v[88:91]
	v_mfma_f32_16x16x32_bf16 v[76:79], v[138:141], v[212:215], v[76:79]
	v_mfma_f32_16x16x32_bf16 v[72:75], v[158:161], v[212:215], v[72:75]
	v_mfma_f32_16x16x32_bf16 v[124:127], v[154:157], v[186:189], v[124:127]
	v_mfma_f32_16x16x32_bf16 v[120:123], v[162:165], v[186:189], v[120:123]
	v_mfma_f32_16x16x32_bf16 v[108:111], v[154:157], v[194:197], v[108:111]
	v_mfma_f32_16x16x32_bf16 v[104:107], v[162:165], v[194:197], v[104:107]
	v_mfma_f32_16x16x32_bf16 v[92:95], v[154:157], v[202:205], v[92:95]
	v_mfma_f32_16x16x32_bf16 v[88:91], v[162:165], v[202:205], v[88:91]
	v_mfma_f32_16x16x32_bf16 v[76:79], v[154:157], v[220:223], v[76:79]
	v_mfma_f32_16x16x32_bf16 v[72:75], v[162:165], v[220:223], v[72:75]
	v_mfma_f32_16x16x32_bf16 v[116:119], v[166:169], v[182:185], v[116:119]
	v_mfma_f32_16x16x32_bf16 v[112:115], v[174:177], v[182:185], v[112:115]
	v_mfma_f32_16x16x32_bf16 v[100:103], v[166:169], v[190:193], v[100:103]
	v_mfma_f32_16x16x32_bf16 v[96:99], v[174:177], v[190:193], v[96:99]
	v_mfma_f32_16x16x32_bf16 v[84:87], v[166:169], v[198:201], v[84:87]
	v_mfma_f32_16x16x32_bf16 v[80:83], v[174:177], v[198:201], v[80:83]
	v_mfma_f32_16x16x32_bf16 v[68:71], v[166:169], v[212:215], v[68:71]
	v_mfma_f32_16x16x32_bf16 v[64:67], v[174:177], v[212:215], v[64:67]
	v_mfma_f32_16x16x32_bf16 v[116:119], v[170:173], v[186:189], v[116:119]
	v_mfma_f32_16x16x32_bf16 v[112:115], v[178:181], v[186:189], v[112:115]
	v_mfma_f32_16x16x32_bf16 v[100:103], v[170:173], v[194:197], v[100:103]
	v_mfma_f32_16x16x32_bf16 v[96:99], v[178:181], v[194:197], v[96:99]
	v_mfma_f32_16x16x32_bf16 v[84:87], v[170:173], v[202:205], v[84:87]
	v_mfma_f32_16x16x32_bf16 v[80:83], v[178:181], v[202:205], v[80:83]
	v_mfma_f32_16x16x32_bf16 v[68:71], v[170:173], v[220:223], v[68:71]
	v_mfma_f32_16x16x32_bf16 v[64:67], v[178:181], v[220:223], v[64:67]
	s_barrier
	s_add_i32 s49, s49, s30
	v_lshl_add_u64 v[142:143], s[20:21], 0, v[148:149]
	s_mov_b32 m0, s49
	ds_read_b128 v[182:185], v145 offset:16384
	ds_read_b128 v[186:189], v145 offset:17408
	ds_read_b128 v[190:193], v145 offset:18432
	ds_read_b128 v[194:197], v145 offset:19456
	ds_read_b128 v[198:201], v145 offset:20480
	ds_read_b128 v[202:205], v145 offset:21504
	ds_read_b128 v[212:215], v145 offset:22528
	ds_read_b128 v[220:223], v145 offset:23552
	global_load_lds_dwordx4 v[142:143], off
	s_add_i32 m0, s49, 0x2000
	s_add_u32 s50, s20, 0x40000
	v_lshl_add_u64 v[146:147], s[20:21], 0, v[128:129]
	s_addc_u32 s51, s21, 0
	s_add_i32 s49, s52, s30
	global_load_lds_dwordx4 v[146:147], off
	v_lshl_add_u64 v[150:151], s[50:51], 0, v[148:149]
	s_mov_b32 m0, s49
	v_lshl_add_u64 v[152:153], s[22:23], 0, v[130:131]
	global_load_lds_dwordx4 v[150:151], off
	v_lshl_add_u64 v[150:151], s[50:51], 0, v[128:129]
	s_add_i32 m0, s49, 0x2000
	s_nop 0
	global_load_lds_dwordx4 v[150:151], off
	v_lshl_add_u64 v[150:151], s[22:23], 0, v[132:133]
	s_mov_b32 m0, s31
	s_nop 0
	global_load_lds_dwordx4 v[150:151], off
	s_mov_b32 m0, s33
	s_nop 0
	global_load_lds_dwordx4 v[152:153], off
	s_waitcnt vmcnt(8)
	s_waitcnt lgkmcnt(0)
	s_barrier
	s_waitcnt lgkmcnt(0)
	v_mfma_f32_16x16x32_bf16 v[60:63], v[138:141], v[182:185], v[60:63]
	v_mfma_f32_16x16x32_bf16 v[56:59], v[158:161], v[182:185], v[56:59]
	v_mfma_f32_16x16x32_bf16 v[44:47], v[138:141], v[190:193], v[44:47]
	v_mfma_f32_16x16x32_bf16 v[40:43], v[158:161], v[190:193], v[40:43]
	v_mfma_f32_16x16x32_bf16 v[28:31], v[138:141], v[198:201], v[28:31]
	v_mfma_f32_16x16x32_bf16 v[24:27], v[158:161], v[198:201], v[24:27]
	v_mfma_f32_16x16x32_bf16 v[12:15], v[138:141], v[212:215], v[12:15]
	v_mfma_f32_16x16x32_bf16 v[8:11], v[158:161], v[212:215], v[8:11]
	v_mfma_f32_16x16x32_bf16 v[60:63], v[154:157], v[186:189], v[60:63]
	v_mfma_f32_16x16x32_bf16 v[56:59], v[162:165], v[186:189], v[56:59]
	v_mfma_f32_16x16x32_bf16 v[44:47], v[154:157], v[194:197], v[44:47]
	v_mfma_f32_16x16x32_bf16 v[40:43], v[162:165], v[194:197], v[40:43]
	v_mfma_f32_16x16x32_bf16 v[28:31], v[154:157], v[202:205], v[28:31]
	v_mfma_f32_16x16x32_bf16 v[24:27], v[162:165], v[202:205], v[24:27]
	v_mfma_f32_16x16x32_bf16 v[12:15], v[154:157], v[220:223], v[12:15]
	v_mfma_f32_16x16x32_bf16 v[8:11], v[162:165], v[220:223], v[8:11]
	v_mfma_f32_16x16x32_bf16 v[52:55], v[166:169], v[182:185], v[52:55]
	v_mfma_f32_16x16x32_bf16 v[48:51], v[174:177], v[182:185], v[48:51]
	v_mfma_f32_16x16x32_bf16 v[36:39], v[166:169], v[190:193], v[36:39]
	v_mfma_f32_16x16x32_bf16 v[32:35], v[174:177], v[190:193], v[32:35]
	v_mfma_f32_16x16x32_bf16 v[20:23], v[166:169], v[198:201], v[20:23]
	v_mfma_f32_16x16x32_bf16 v[16:19], v[174:177], v[198:201], v[16:19]
	v_mfma_f32_16x16x32_bf16 v[4:7], v[166:169], v[212:215], v[4:7]
	v_mfma_f32_16x16x32_bf16 v[0:3], v[174:177], v[212:215], v[0:3]
	v_mfma_f32_16x16x32_bf16 v[52:55], v[170:173], v[186:189], v[52:55]
	v_mfma_f32_16x16x32_bf16 v[48:51], v[178:181], v[186:189], v[48:51]
	v_mfma_f32_16x16x32_bf16 v[36:39], v[170:173], v[194:197], v[36:39]
	v_mfma_f32_16x16x32_bf16 v[32:35], v[178:181], v[194:197], v[32:35]
	v_mfma_f32_16x16x32_bf16 v[20:23], v[170:173], v[202:205], v[20:23]
	v_mfma_f32_16x16x32_bf16 v[16:19], v[178:181], v[202:205], v[16:19]
	v_mfma_f32_16x16x32_bf16 v[4:7], v[170:173], v[220:223], v[4:7]
	v_mfma_f32_16x16x32_bf16 v[0:3], v[178:181], v[220:223], v[0:3]
	s_barrier
	s_add_i32 s49, 0, 0x18000
	s_add_i32 s50, 0, 0x1c000
	v_add_u32_e32 v162, s49, v144
	v_add_u32_e32 v178, s50, v144
	ds_read_b128 v[138:141], v162
	ds_read_b128 v[154:157], v162 offset:1024
	ds_read_b128 v[158:161], v162 offset:2048
	ds_read_b128 v[162:165], v162 offset:3072
	ds_read_b128 v[166:169], v178
	ds_read_b128 v[170:173], v178 offset:1024
	ds_read_b128 v[174:177], v178 offset:2048
	ds_read_b128 v[178:181], v178 offset:3072
	s_add_u32 s22, s22, 0x40000
	s_addc_u32 s23, s23, 0
	s_mov_b32 m0, s34
	v_lshl_add_u64 v[208:209], s[22:23], 0, v[132:133]
	ds_read_b128 v[182:185], v145 offset:32768
	ds_read_b128 v[186:189], v145 offset:33792
	ds_read_b128 v[190:193], v145 offset:34816
	ds_read_b128 v[194:197], v145 offset:35840
	ds_read_b128 v[198:201], v145 offset:36864
	ds_read_b128 v[202:205], v145 offset:37888
	ds_read_b128 v[212:215], v145 offset:38912
	ds_read_b128 v[220:223], v145 offset:39936
	global_load_lds_dwordx4 v[208:209], off
	v_lshl_add_u64 v[208:209], s[22:23], 0, v[130:131]
	s_mov_b32 m0, s35
	s_nop 0
	global_load_lds_dwordx4 v[208:209], off
	s_waitcnt vmcnt(8)
	s_waitcnt lgkmcnt(0)
	s_barrier
	s_waitcnt lgkmcnt(0)
	v_mfma_f32_16x16x32_bf16 v[124:127], v[138:141], v[182:185], v[124:127]
	v_mfma_f32_16x16x32_bf16 v[120:123], v[158:161], v[182:185], v[120:123]
	v_mfma_f32_16x16x32_bf16 v[108:111], v[138:141], v[190:193], v[108:111]
	v_mfma_f32_16x16x32_bf16 v[104:107], v[158:161], v[190:193], v[104:107]
	v_mfma_f32_16x16x32_bf16 v[92:95], v[138:141], v[198:201], v[92:95]
	v_mfma_f32_16x16x32_bf16 v[88:91], v[158:161], v[198:201], v[88:91]
	v_mfma_f32_16x16x32_bf16 v[76:79], v[138:141], v[212:215], v[76:79]
	v_mfma_f32_16x16x32_bf16 v[72:75], v[158:161], v[212:215], v[72:75]
	v_mfma_f32_16x16x32_bf16 v[124:127], v[154:157], v[186:189], v[124:127]
	v_mfma_f32_16x16x32_bf16 v[120:123], v[162:165], v[186:189], v[120:123]
	v_mfma_f32_16x16x32_bf16 v[108:111], v[154:157], v[194:197], v[108:111]
	v_mfma_f32_16x16x32_bf16 v[104:107], v[162:165], v[194:197], v[104:107]
	v_mfma_f32_16x16x32_bf16 v[92:95], v[154:157], v[202:205], v[92:95]
	v_mfma_f32_16x16x32_bf16 v[88:91], v[162:165], v[202:205], v[88:91]
	v_mfma_f32_16x16x32_bf16 v[76:79], v[154:157], v[220:223], v[76:79]
	v_mfma_f32_16x16x32_bf16 v[72:75], v[162:165], v[220:223], v[72:75]
	v_mfma_f32_16x16x32_bf16 v[116:119], v[166:169], v[182:185], v[116:119]
	v_mfma_f32_16x16x32_bf16 v[112:115], v[174:177], v[182:185], v[112:115]
	v_mfma_f32_16x16x32_bf16 v[100:103], v[166:169], v[190:193], v[100:103]
	v_mfma_f32_16x16x32_bf16 v[96:99], v[174:177], v[190:193], v[96:99]
	v_mfma_f32_16x16x32_bf16 v[84:87], v[166:169], v[198:201], v[84:87]
	v_mfma_f32_16x16x32_bf16 v[80:83], v[174:177], v[198:201], v[80:83]
	v_mfma_f32_16x16x32_bf16 v[68:71], v[166:169], v[212:215], v[68:71]
	v_mfma_f32_16x16x32_bf16 v[64:67], v[174:177], v[212:215], v[64:67]
	v_mfma_f32_16x16x32_bf16 v[116:119], v[170:173], v[186:189], v[116:119]
	v_mfma_f32_16x16x32_bf16 v[112:115], v[178:181], v[186:189], v[112:115]
	v_mfma_f32_16x16x32_bf16 v[100:103], v[170:173], v[194:197], v[100:103]
	v_mfma_f32_16x16x32_bf16 v[96:99], v[178:181], v[194:197], v[96:99]
	v_mfma_f32_16x16x32_bf16 v[84:87], v[170:173], v[202:205], v[84:87]
	v_mfma_f32_16x16x32_bf16 v[80:83], v[178:181], v[202:205], v[80:83]
	v_mfma_f32_16x16x32_bf16 v[68:71], v[170:173], v[220:223], v[68:71]
	v_mfma_f32_16x16x32_bf16 v[64:67], v[178:181], v[220:223], v[64:67]
	s_barrier
	s_add_i32 s22, s49, s30
	v_lshl_add_u64 v[142:143], v[142:143], 0, s[28:29]
	s_mov_b32 m0, s22
	ds_read_b128 v[182:185], v145 offset:49152
	ds_read_b128 v[186:189], v145 offset:50176
	ds_read_b128 v[190:193], v145 offset:51200
	ds_read_b128 v[194:197], v145 offset:52224
	ds_read_b128 v[198:201], v145 offset:53248
	ds_read_b128 v[202:205], v145 offset:54272
	ds_read_b128 v[212:215], v145 offset:55296
	ds_read_b128 v[220:223], v145 offset:56320
	global_load_lds_dwordx4 v[142:143], off
	s_add_i32 m0, s22, 0x2000
	s_add_u32 s20, s20, 0x40080
	v_lshl_add_u64 v[142:143], v[146:147], 0, s[28:29]
	s_addc_u32 s21, s21, 0
	s_add_i32 s22, s50, s30
	global_load_lds_dwordx4 v[142:143], off
	v_lshl_add_u64 v[142:143], s[20:21], 0, v[148:149]
	s_mov_b32 m0, s22
	s_nop 0
	global_load_lds_dwordx4 v[142:143], off
	v_lshl_add_u64 v[142:143], s[20:21], 0, v[128:129]
	s_add_i32 m0, s22, 0x2000
	s_nop 0
	global_load_lds_dwordx4 v[142:143], off
	v_lshl_add_u64 v[142:143], v[150:151], 0, s[28:29]
	s_mov_b32 m0, s39
	s_nop 0
	global_load_lds_dwordx4 v[142:143], off
	v_lshl_add_u64 v[142:143], v[152:153], 0, s[28:29]
	s_mov_b32 m0, s40
	s_nop 0
	global_load_lds_dwordx4 v[142:143], off
	s_waitcnt vmcnt(8)
	s_waitcnt lgkmcnt(0)
	s_barrier
	s_waitcnt lgkmcnt(0)
	v_mfma_f32_16x16x32_bf16 v[60:63], v[138:141], v[182:185], v[60:63]
	v_mfma_f32_16x16x32_bf16 v[56:59], v[158:161], v[182:185], v[56:59]
	v_mfma_f32_16x16x32_bf16 v[44:47], v[138:141], v[190:193], v[44:47]
	v_mfma_f32_16x16x32_bf16 v[40:43], v[158:161], v[190:193], v[40:43]
	v_mfma_f32_16x16x32_bf16 v[28:31], v[138:141], v[198:201], v[28:31]
	v_mfma_f32_16x16x32_bf16 v[24:27], v[158:161], v[198:201], v[24:27]
	v_mfma_f32_16x16x32_bf16 v[12:15], v[138:141], v[212:215], v[12:15]
	v_mfma_f32_16x16x32_bf16 v[8:11], v[158:161], v[212:215], v[8:11]
	v_mfma_f32_16x16x32_bf16 v[60:63], v[154:157], v[186:189], v[60:63]
	v_mfma_f32_16x16x32_bf16 v[56:59], v[162:165], v[186:189], v[56:59]
	v_mfma_f32_16x16x32_bf16 v[44:47], v[154:157], v[194:197], v[44:47]
	v_mfma_f32_16x16x32_bf16 v[40:43], v[162:165], v[194:197], v[40:43]
	v_mfma_f32_16x16x32_bf16 v[28:31], v[154:157], v[202:205], v[28:31]
	v_mfma_f32_16x16x32_bf16 v[24:27], v[162:165], v[202:205], v[24:27]
	v_mfma_f32_16x16x32_bf16 v[12:15], v[154:157], v[220:223], v[12:15]
	v_mfma_f32_16x16x32_bf16 v[8:11], v[162:165], v[220:223], v[8:11]
	v_mfma_f32_16x16x32_bf16 v[52:55], v[166:169], v[182:185], v[52:55]
	v_mfma_f32_16x16x32_bf16 v[48:51], v[174:177], v[182:185], v[48:51]
	v_mfma_f32_16x16x32_bf16 v[36:39], v[166:169], v[190:193], v[36:39]
	v_mfma_f32_16x16x32_bf16 v[32:35], v[174:177], v[190:193], v[32:35]
	v_mfma_f32_16x16x32_bf16 v[20:23], v[166:169], v[198:201], v[20:23]
	v_mfma_f32_16x16x32_bf16 v[16:19], v[174:177], v[198:201], v[16:19]
	v_mfma_f32_16x16x32_bf16 v[4:7], v[166:169], v[212:215], v[4:7]
	v_mfma_f32_16x16x32_bf16 v[0:3], v[174:177], v[212:215], v[0:3]
	v_mfma_f32_16x16x32_bf16 v[52:55], v[170:173], v[186:189], v[52:55]
	v_mfma_f32_16x16x32_bf16 v[48:51], v[178:181], v[186:189], v[48:51]
	v_mfma_f32_16x16x32_bf16 v[36:39], v[170:173], v[194:197], v[36:39]
	v_mfma_f32_16x16x32_bf16 v[32:35], v[178:181], v[194:197], v[32:35]
	v_mfma_f32_16x16x32_bf16 v[20:23], v[170:173], v[202:205], v[20:23]
	v_mfma_f32_16x16x32_bf16 v[16:19], v[178:181], v[202:205], v[16:19]
	v_mfma_f32_16x16x32_bf16 v[4:7], v[170:173], v[220:223], v[4:7]
	v_mfma_f32_16x16x32_bf16 v[0:3], v[178:181], v[220:223], v[0:3]
	s_barrier
	s_add_i32 s48, s48, 2
	s_add_u32 s18, s18, 0x100
	s_addc_u32 s19, s19, 0
	s_add_u32 s46, s46, 0x100
	s_addc_u32 s47, s47, 0
	s_cmp_gt_u32 s48, 13
	s_cbranch_scc0 .LBB0_1438
	s_setprio 0
	s_and_b64 vcc, exec, s[8:9]
	s_cbranch_vccz .LBB0_1441
	s_barrier
